# redundant post-barrier lgkmcnt wait removed in the K loops, on top of the K-loop s_setprio removal
# speedup vs baseline: 1.0162x; 1.0020x over previous
; #define PG8_STAGE(bufoff, gbase, voff) do { _Pragma("unroll") for (int _i = 0; _i < 2; ++_i) \
;         __builtin_amdgcn_global_load_lds((const unsigned*)((const char*)(gbase) + (voff)[_i]), (LAS unsigned*)(lds + (bufoff) + ldsw + _i * 8192), 16, 0, 0); } while (0)
; #define PG8_LDA(dst, b, h) do { _Pragma("unroll") for (int m = 0; m < 4; ++m) _Pragma("unroll") for (int k = 0; k < 2; ++k) dst[m][k] = *(const LAS bf16x8*)(lds + PG8_SA(b, h) + aoff + m * 2048 + k * 1024); } while (0)
; #define PG8_LDB(dst, b, h) do { _Pragma("unroll") for (int n = 0; n < 2; ++n) _Pragma("unroll") for (int k = 0; k < 2; ++k) dst[n][k] = *(const LAS bf16x8*)(lds + PG8_SB(b, h) + boff + n * 2048 + k * 1024); } while (0)
; #define PG8_MMA(ai, bj, At, Bt) do { __builtin_amdgcn_s_setprio(1); _Pragma("unroll") for (int m = 0; m < 4; ++m) _Pragma("unroll") for (int n = 0; n < 2; ++n) _Pragma("unroll") for (int k = 0; k < 2; ++k) \
;         acc[ai][bj][m][n] = __builtin_amdgcn_mfma_f32_16x16x32_bf16(Bt[n][k], At[m][k], acc[ai][bj][m][n], 0, 0, 0); __builtin_amdgcn_s_setprio(0); } while (0)
; #define PG8_WAIT_V(n) asm volatile("s_waitcnt vmcnt(" #n ")" ::: "memory")
; #define PG8_WAIT_L(n) asm volatile("s_waitcnt lgkmcnt(" #n ")" ::: "memory")
; #define PG8_BAR __builtin_amdgcn_s_barrier()
; #define PG8_SCHED __builtin_amdgcn_sched_barrier(0)
;     DI void a_ready(const Unit& u) const { if (ctr && u.pm >= 128) wait_counter(ctr, target); }
; template <class Epi, class Sched>
; DI void gemm_phase(LAS unsigned char* lds, const int K, const Sched& S, const Epi& E, const int wid) {
;     ...
;         for (int t = 0; t < nt; t += 2) {
;             const bool last = (t == nt - 2);
;             const char* a1 = cA + (size_t)(t + 1) * kstep;
;             const char* a2 = last ? nA : cA + (size_t)(t + 2) * kstep; const char* b2 = last ? nB : cB + (size_t)(t + 2) * kstep;
;             const char* a3 = a2 + kstep; const char* b3 = b2 + kstep;
;             if (last && has_next) S.a_ready(nxt);
;             PG8_LDB(B0, 0, 0); PG8_LDB(B1, 0, 1); PG8_SCHED; PG8_LDA(At, 0, 0); PG8_STAGE(PG8_SA(1, 1), a1 + hstep, voffA);
;             PG8_WAIT_V(8); PG8_WAIT_L(0); PG8_BAR; PG8_MMA(0, 0, At, B0); PG8_MMA(0, 1, At, B1); PG8_BAR; PG8_SCHED;
;             PG8_LDA(At, 0, 1); PG8_STAGE(PG8_SB(0, 0), b2, voffB); PG8_STAGE(PG8_SB(0, 1), b2 + hstep, voffB); PG8_STAGE(PG8_SA(0, 0), a2, voffA);
.LBB0_96:
	ds_read_b128 v[128:131], v179
	ds_read_b128 v[132:135], v179 offset:1024
	ds_read_b128 v[136:139], v179 offset:2048
	ds_read_b128 v[140:143], v179 offset:3072
	ds_read_b128 v[144:147], v180
	ds_read_b128 v[164:167], v180 offset:1024
	ds_read_b128 v[168:171], v180 offset:2048
	ds_read_b128 v[172:175], v180 offset:3072
	s_add_u32 s18, s4, 0xfff80080
	s_addc_u32 s19, s5, -1
	s_cmp_eq_u32 s17, 28
	s_cselect_b32 s69, s9, s19
	s_cselect_b32 s68, s10, s18
	s_cselect_b32 s57, s11, s16
	s_cselect_b32 s56, s14, s15
	v_lshl_add_u64 v[204:205], s[4:5], 0, v[156:157]
	s_add_i32 m0, s22, 0xc000
	ds_read_b128 v[184:187], v181
	ds_read_b128 v[188:191], v181 offset:1024
	ds_read_b128 v[192:195], v181 offset:2048
	ds_read_b128 v[196:199], v181 offset:3072
	ds_read_b128 v[200:203], v181 offset:4096
	ds_read_b128 v[208:211], v181 offset:5120
	ds_read_b128 v[212:215], v181 offset:6144
	ds_read_b128 v[216:219], v181 offset:7168
	global_load_lds_dwordx4 v[204:205], off
	v_lshl_add_u64 v[204:205], s[4:5], 0, v[158:159]
	s_add_i32 m0, s22, 0xe000
	s_nop 0
	global_load_lds_dwordx4 v[204:205], off
	s_waitcnt vmcnt(8)
	s_waitcnt lgkmcnt(0)
	s_barrier
	v_mfma_f32_16x16x32_bf16 v[124:127], v[128:131], v[184:187], v[124:127]
	v_mfma_f32_16x16x32_bf16 v[120:123], v[136:139], v[184:187], v[120:123]
	v_mfma_f32_16x16x32_bf16 v[116:119], v[128:131], v[192:195], v[116:119]
	v_mfma_f32_16x16x32_bf16 v[112:115], v[136:139], v[192:195], v[112:115]
	v_mfma_f32_16x16x32_bf16 v[100:103], v[128:131], v[200:203], v[100:103]
	v_mfma_f32_16x16x32_bf16 v[96:99], v[136:139], v[200:203], v[96:99]
	v_mfma_f32_16x16x32_bf16 v[84:87], v[128:131], v[212:215], v[84:87]
	v_mfma_f32_16x16x32_bf16 v[80:83], v[136:139], v[212:215], v[80:83]
	v_mfma_f32_16x16x32_bf16 v[124:127], v[132:135], v[188:191], v[124:127]
	v_mfma_f32_16x16x32_bf16 v[120:123], v[140:143], v[188:191], v[120:123]
	v_mfma_f32_16x16x32_bf16 v[116:119], v[132:135], v[196:199], v[116:119]
	v_mfma_f32_16x16x32_bf16 v[112:115], v[140:143], v[196:199], v[112:115]
	v_mfma_f32_16x16x32_bf16 v[100:103], v[132:135], v[208:211], v[100:103]
	v_mfma_f32_16x16x32_bf16 v[96:99], v[140:143], v[208:211], v[96:99]
	v_mfma_f32_16x16x32_bf16 v[84:87], v[132:135], v[216:219], v[84:87]
	v_mfma_f32_16x16x32_bf16 v[80:83], v[140:143], v[216:219], v[80:83]
	v_mfma_f32_16x16x32_bf16 v[108:111], v[144:147], v[184:187], v[108:111]
	v_mfma_f32_16x16x32_bf16 v[104:107], v[168:171], v[184:187], v[104:107]
	v_mfma_f32_16x16x32_bf16 v[92:95], v[144:147], v[192:195], v[92:95]
	v_mfma_f32_16x16x32_bf16 v[88:91], v[168:171], v[192:195], v[88:91]
	v_mfma_f32_16x16x32_bf16 v[76:79], v[144:147], v[200:203], v[76:79]
	v_mfma_f32_16x16x32_bf16 v[72:75], v[168:171], v[200:203], v[72:75]
	v_mfma_f32_16x16x32_bf16 v[68:71], v[144:147], v[212:215], v[68:71]
	v_mfma_f32_16x16x32_bf16 v[64:67], v[168:171], v[212:215], v[64:67]
	v_mfma_f32_16x16x32_bf16 v[108:111], v[164:167], v[188:191], v[108:111]
	v_mfma_f32_16x16x32_bf16 v[104:107], v[172:175], v[188:191], v[104:107]
	v_mfma_f32_16x16x32_bf16 v[92:95], v[164:167], v[196:199], v[92:95]
	v_mfma_f32_16x16x32_bf16 v[88:91], v[172:175], v[196:199], v[88:91]
	v_mfma_f32_16x16x32_bf16 v[76:79], v[164:167], v[208:211], v[76:79]
	v_mfma_f32_16x16x32_bf16 v[72:75], v[172:175], v[208:211], v[72:75]
	v_mfma_f32_16x16x32_bf16 v[68:71], v[164:167], v[216:219], v[68:71]
	v_mfma_f32_16x16x32_bf16 v[64:67], v[172:175], v[216:219], v[64:67]
	s_barrier
	s_add_i32 s18, s13, s95
	v_lshl_add_u64 v[204:205], s[56:57], 0, v[150:151]
	s_mov_b32 m0, s18
	ds_read_b128 v[184:187], v181 offset:16384
	ds_read_b128 v[188:191], v181 offset:17408
	ds_read_b128 v[192:195], v181 offset:18432
	ds_read_b128 v[196:199], v181 offset:19456
	ds_read_b128 v[200:203], v181 offset:20480
	ds_read_b128 v[208:211], v181 offset:21504
	ds_read_b128 v[212:215], v181 offset:22528
	ds_read_b128 v[216:219], v181 offset:23552
	global_load_lds_dwordx4 v[204:205], off
	s_add_i32 m0, s18, 0x2000
	s_add_u32 s18, s56, 0x80000
	v_lshl_add_u64 v[220:221], s[56:57], 0, v[154:155]
	s_addc_u32 s19, s57, 0
	s_add_i32 s20, s24, s95
	global_load_lds_dwordx4 v[220:221], off
	v_lshl_add_u64 v[222:223], s[18:19], 0, v[150:151]
	s_mov_b32 m0, s20
	v_lshl_add_u64 v[224:225], s[68:69], 0, v[152:153]
	global_load_lds_dwordx4 v[222:223], off
	v_lshl_add_u64 v[222:223], s[18:19], 0, v[154:155]
	s_add_i32 m0, s20, 0x2000
	s_nop 0
	global_load_lds_dwordx4 v[222:223], off
	v_lshl_add_u64 v[222:223], s[68:69], 0, v[148:149]
	s_mov_b32 m0, s22
	s_nop 0
	global_load_lds_dwordx4 v[222:223], off
	s_mov_b32 m0, s23
	s_nop 0
	global_load_lds_dwordx4 v[224:225], off
	s_waitcnt vmcnt(8)
	s_waitcnt lgkmcnt(0)
	s_barrier
; #define PG8_STAGE(bufoff, gbase, voff) do { _Pragma("unroll") for (int _i = 0; _i < 2; ++_i) \
;         __builtin_amdgcn_global_load_lds((const unsigned*)((const char*)(gbase) + (voff)[_i]), (LAS unsigned*)(lds + (bufoff) + ldsw + _i * 8192), 16, 0, 0); } while (0)
; #define PG8_LDA(dst, b, h) do { _Pragma("unroll") for (int m = 0; m < 4; ++m) _Pragma("unroll") for (int k = 0; k < 2; ++k) dst[m][k] = *(const LAS bf16x8*)(lds + PG8_SA(b, h) + aoff + m * 2048 + k * 1024); } while (0)
; #define PG8_LDB(dst, b, h) do { _Pragma("unroll") for (int n = 0; n < 2; ++n) _Pragma("unroll") for (int k = 0; k < 2; ++k) dst[n][k] = *(const LAS bf16x8*)(lds + PG8_SB(b, h) + boff + n * 2048 + k * 1024); } while (0)
; #define PG8_MMA(ai, bj, At, Bt) do { __builtin_amdgcn_s_setprio(1); _Pragma("unroll") for (int m = 0; m < 4; ++m) _Pragma("unroll") for (int n = 0; n < 2; ++n) _Pragma("unroll") for (int k = 0; k < 2; ++k) \
;         acc[ai][bj][m][n] = __builtin_amdgcn_mfma_f32_16x16x32_bf16(Bt[n][k], At[m][k], acc[ai][bj][m][n], 0, 0, 0); __builtin_amdgcn_s_setprio(0); } while (0)
; #define PG8_WAIT_V(n) asm volatile("s_waitcnt vmcnt(" #n ")" ::: "memory")
; #define PG8_WAIT_L(n) asm volatile("s_waitcnt lgkmcnt(" #n ")" ::: "memory")
; #define PG8_BAR __builtin_amdgcn_s_barrier()
; #define PG8_SCHED __builtin_amdgcn_sched_barrier(0)
; template <class Epi, class Sched>
; DI void gemm_phase(LAS unsigned char* lds, const int K, const Sched& S, const Epi& E, const int wid) {
;     ...
;             PG8_WAIT_V(8); PG8_WAIT_L(0); PG8_BAR; PG8_MMA(1, 0, At, B0); PG8_MMA(1, 1, At, B1); PG8_BAR; PG8_SCHED;
;             PG8_LDB(B0, 1, 0); PG8_LDB(B1, 1, 1); PG8_SCHED; PG8_LDA(At, 1, 0); PG8_STAGE(PG8_SA(0, 1), a2 + hstep, voffA);
;             PG8_WAIT_V(8); PG8_WAIT_L(0); PG8_BAR; PG8_MMA(0, 0, At, B0); PG8_MMA(0, 1, At, B1); PG8_BAR; PG8_SCHED;
	v_mfma_f32_16x16x32_bf16 v[60:63], v[128:131], v[184:187], v[60:63]
	v_mfma_f32_16x16x32_bf16 v[56:59], v[136:139], v[184:187], v[56:59]
	v_mfma_f32_16x16x32_bf16 v[52:55], v[128:131], v[192:195], v[52:55]
	v_mfma_f32_16x16x32_bf16 v[48:51], v[136:139], v[192:195], v[48:51]
	v_mfma_f32_16x16x32_bf16 v[36:39], v[128:131], v[200:203], v[36:39]
	v_mfma_f32_16x16x32_bf16 v[32:35], v[136:139], v[200:203], v[32:35]
	v_mfma_f32_16x16x32_bf16 v[20:23], v[128:131], v[212:215], v[20:23]
	v_mfma_f32_16x16x32_bf16 v[16:19], v[136:139], v[212:215], v[16:19]
	v_mfma_f32_16x16x32_bf16 v[60:63], v[132:135], v[188:191], v[60:63]
	v_mfma_f32_16x16x32_bf16 v[56:59], v[140:143], v[188:191], v[56:59]
	v_mfma_f32_16x16x32_bf16 v[52:55], v[132:135], v[196:199], v[52:55]
	v_mfma_f32_16x16x32_bf16 v[48:51], v[140:143], v[196:199], v[48:51]
	v_mfma_f32_16x16x32_bf16 v[36:39], v[132:135], v[208:211], v[36:39]
	v_mfma_f32_16x16x32_bf16 v[32:35], v[140:143], v[208:211], v[32:35]
	v_mfma_f32_16x16x32_bf16 v[20:23], v[132:135], v[216:219], v[20:23]
	v_mfma_f32_16x16x32_bf16 v[16:19], v[140:143], v[216:219], v[16:19]
	v_mfma_f32_16x16x32_bf16 v[44:47], v[144:147], v[184:187], v[44:47]
	v_mfma_f32_16x16x32_bf16 v[40:43], v[168:171], v[184:187], v[40:43]
	v_mfma_f32_16x16x32_bf16 v[28:31], v[144:147], v[192:195], v[28:31]
	v_mfma_f32_16x16x32_bf16 v[24:27], v[168:171], v[192:195], v[24:27]
	v_mfma_f32_16x16x32_bf16 v[12:15], v[144:147], v[200:203], v[12:15]
	v_mfma_f32_16x16x32_bf16 v[8:11], v[168:171], v[200:203], v[8:11]
	v_mfma_f32_16x16x32_bf16 v[4:7], v[144:147], v[212:215], v[4:7]
	v_mfma_f32_16x16x32_bf16 v[0:3], v[168:171], v[212:215], v[0:3]
	v_mfma_f32_16x16x32_bf16 v[44:47], v[164:167], v[188:191], v[44:47]
	v_mfma_f32_16x16x32_bf16 v[40:43], v[172:175], v[188:191], v[40:43]
	v_mfma_f32_16x16x32_bf16 v[28:31], v[164:167], v[196:199], v[28:31]
	v_mfma_f32_16x16x32_bf16 v[24:27], v[172:175], v[196:199], v[24:27]
	v_mfma_f32_16x16x32_bf16 v[12:15], v[164:167], v[208:211], v[12:15]
	v_mfma_f32_16x16x32_bf16 v[8:11], v[172:175], v[208:211], v[8:11]
	v_mfma_f32_16x16x32_bf16 v[4:7], v[164:167], v[216:219], v[4:7]
	v_mfma_f32_16x16x32_bf16 v[0:3], v[172:175], v[216:219], v[0:3]
	s_barrier
	s_add_i32 s20, 0, 0x18000
	s_add_i32 s21, 0, 0x1c000
	v_add_u32_e32 v140, s20, v178
	v_add_u32_e32 v172, s21, v178
	ds_read_b128 v[128:131], v140
	ds_read_b128 v[132:135], v140 offset:1024
	ds_read_b128 v[136:139], v140 offset:2048
	ds_read_b128 v[140:143], v140 offset:3072
	ds_read_b128 v[144:147], v172
	ds_read_b128 v[164:167], v172 offset:1024
	ds_read_b128 v[168:171], v172 offset:2048
	ds_read_b128 v[172:175], v172 offset:3072
	s_add_u32 s18, s68, 0x80000
	s_addc_u32 s19, s69, 0
	s_mov_b32 m0, s26
	v_lshl_add_u64 v[226:227], s[18:19], 0, v[148:149]
	ds_read_b128 v[184:187], v181 offset:32768
	ds_read_b128 v[188:191], v181 offset:33792
	ds_read_b128 v[192:195], v181 offset:34816
	ds_read_b128 v[196:199], v181 offset:35840
	ds_read_b128 v[200:203], v181 offset:36864
	ds_read_b128 v[208:211], v181 offset:37888
	ds_read_b128 v[212:215], v181 offset:38912
	ds_read_b128 v[216:219], v181 offset:39936
	global_load_lds_dwordx4 v[226:227], off
	v_lshl_add_u64 v[226:227], s[18:19], 0, v[152:153]
	s_mov_b32 m0, s27
	s_nop 0
	global_load_lds_dwordx4 v[226:227], off
	s_waitcnt vmcnt(8)
	s_waitcnt lgkmcnt(0)
	s_barrier
	v_mfma_f32_16x16x32_bf16 v[124:127], v[128:131], v[184:187], v[124:127]
	v_mfma_f32_16x16x32_bf16 v[120:123], v[136:139], v[184:187], v[120:123]
	v_mfma_f32_16x16x32_bf16 v[116:119], v[128:131], v[192:195], v[116:119]
	v_mfma_f32_16x16x32_bf16 v[112:115], v[136:139], v[192:195], v[112:115]
	v_mfma_f32_16x16x32_bf16 v[100:103], v[128:131], v[200:203], v[100:103]
	v_mfma_f32_16x16x32_bf16 v[96:99], v[136:139], v[200:203], v[96:99]
	v_mfma_f32_16x16x32_bf16 v[84:87], v[128:131], v[212:215], v[84:87]
	v_mfma_f32_16x16x32_bf16 v[80:83], v[136:139], v[212:215], v[80:83]
	v_mfma_f32_16x16x32_bf16 v[124:127], v[132:135], v[188:191], v[124:127]
	v_mfma_f32_16x16x32_bf16 v[120:123], v[140:143], v[188:191], v[120:123]
	v_mfma_f32_16x16x32_bf16 v[116:119], v[132:135], v[196:199], v[116:119]
	v_mfma_f32_16x16x32_bf16 v[112:115], v[140:143], v[196:199], v[112:115]
	v_mfma_f32_16x16x32_bf16 v[100:103], v[132:135], v[208:211], v[100:103]
	v_mfma_f32_16x16x32_bf16 v[96:99], v[140:143], v[208:211], v[96:99]
	v_mfma_f32_16x16x32_bf16 v[84:87], v[132:135], v[216:219], v[84:87]
	v_mfma_f32_16x16x32_bf16 v[80:83], v[140:143], v[216:219], v[80:83]
	v_mfma_f32_16x16x32_bf16 v[108:111], v[144:147], v[184:187], v[108:111]
	v_mfma_f32_16x16x32_bf16 v[104:107], v[168:171], v[184:187], v[104:107]
	v_mfma_f32_16x16x32_bf16 v[92:95], v[144:147], v[192:195], v[92:95]
	v_mfma_f32_16x16x32_bf16 v[88:91], v[168:171], v[192:195], v[88:91]
	v_mfma_f32_16x16x32_bf16 v[76:79], v[144:147], v[200:203], v[76:79]
	v_mfma_f32_16x16x32_bf16 v[72:75], v[168:171], v[200:203], v[72:75]
	v_mfma_f32_16x16x32_bf16 v[68:71], v[144:147], v[212:215], v[68:71]
	v_mfma_f32_16x16x32_bf16 v[64:67], v[168:171], v[212:215], v[64:67]
	v_mfma_f32_16x16x32_bf16 v[108:111], v[164:167], v[188:191], v[108:111]
	v_mfma_f32_16x16x32_bf16 v[104:107], v[172:175], v[188:191], v[104:107]
	v_mfma_f32_16x16x32_bf16 v[92:95], v[164:167], v[196:199], v[92:95]
	v_mfma_f32_16x16x32_bf16 v[88:91], v[172:175], v[196:199], v[88:91]
	v_mfma_f32_16x16x32_bf16 v[76:79], v[164:167], v[208:211], v[76:79]
	v_mfma_f32_16x16x32_bf16 v[72:75], v[172:175], v[208:211], v[72:75]
	v_mfma_f32_16x16x32_bf16 v[68:71], v[164:167], v[216:219], v[68:71]
	v_mfma_f32_16x16x32_bf16 v[64:67], v[172:175], v[216:219], v[64:67]
	s_barrier
; #define PG8_STAGE(bufoff, gbase, voff) do { _Pragma("unroll") for (int _i = 0; _i < 2; ++_i) \
;         __builtin_amdgcn_global_load_lds((const unsigned*)((const char*)(gbase) + (voff)[_i]), (LAS unsigned*)(lds + (bufoff) + ldsw + _i * 8192), 16, 0, 0); } while (0)
; #define PG8_LDA(dst, b, h) do { _Pragma("unroll") for (int m = 0; m < 4; ++m) _Pragma("unroll") for (int k = 0; k < 2; ++k) dst[m][k] = *(const LAS bf16x8*)(lds + PG8_SA(b, h) + aoff + m * 2048 + k * 1024); } while (0)
; #define PG8_MMA(ai, bj, At, Bt) do { __builtin_amdgcn_s_setprio(1); _Pragma("unroll") for (int m = 0; m < 4; ++m) _Pragma("unroll") for (int n = 0; n < 2; ++n) _Pragma("unroll") for (int k = 0; k < 2; ++k) \
;         acc[ai][bj][m][n] = __builtin_amdgcn_mfma_f32_16x16x32_bf16(Bt[n][k], At[m][k], acc[ai][bj][m][n], 0, 0, 0); __builtin_amdgcn_s_setprio(0); } while (0)
; #define PG8_WAIT_V(n) asm volatile("s_waitcnt vmcnt(" #n ")" ::: "memory")
; #define PG8_WAIT_L(n) asm volatile("s_waitcnt lgkmcnt(" #n ")" ::: "memory")
; #define PG8_BAR __builtin_amdgcn_s_barrier()
; #define PG8_SCHED __builtin_amdgcn_sched_barrier(0)
; template <class Epi, class Sched>
; DI void gemm_phase(LAS unsigned char* lds, const int K, const Sched& S, const Epi& E, const int wid) {
;     ...
;             PG8_LDA(At, 1, 1); PG8_STAGE(PG8_SB(1, 0), b3, voffB); PG8_STAGE(PG8_SB(1, 1), b3 + hstep, voffB); PG8_STAGE(PG8_SA(1, 0), a3, voffA);
;             PG8_WAIT_V(8); PG8_WAIT_L(0); PG8_BAR; PG8_MMA(1, 0, At, B0); PG8_MMA(1, 1, At, B1); PG8_BAR; PG8_SCHED;
;         }
	s_add_i32 s18, s20, s95
	v_lshl_add_u64 v[204:205], v[204:205], 0, s[42:43]
	s_mov_b32 m0, s18
	ds_read_b128 v[184:187], v181 offset:49152
	ds_read_b128 v[188:191], v181 offset:50176
	ds_read_b128 v[192:195], v181 offset:51200
	ds_read_b128 v[196:199], v181 offset:52224
	ds_read_b128 v[200:203], v181 offset:53248
	ds_read_b128 v[208:211], v181 offset:54272
	ds_read_b128 v[212:215], v181 offset:55296
	ds_read_b128 v[216:219], v181 offset:56320
	global_load_lds_dwordx4 v[204:205], off
	s_add_i32 m0, s18, 0x2000
	s_add_u32 s18, s56, 0x80080
	v_lshl_add_u64 v[204:205], v[220:221], 0, s[42:43]
	s_addc_u32 s19, s57, 0
	s_add_i32 s20, s21, s95
	global_load_lds_dwordx4 v[204:205], off
	v_lshl_add_u64 v[204:205], s[18:19], 0, v[150:151]
	s_mov_b32 m0, s20
	s_nop 0
	global_load_lds_dwordx4 v[204:205], off
	v_lshl_add_u64 v[204:205], s[18:19], 0, v[154:155]
	s_add_i32 m0, s20, 0x2000
	s_nop 0
	global_load_lds_dwordx4 v[204:205], off
	v_lshl_add_u64 v[204:205], v[222:223], 0, s[42:43]
	s_mov_b32 m0, s94
	s_nop 0
	global_load_lds_dwordx4 v[204:205], off
	v_lshl_add_u64 v[204:205], v[224:225], 0, s[42:43]
	s_mov_b32 m0, s96
	s_nop 0
	global_load_lds_dwordx4 v[204:205], off
	s_waitcnt vmcnt(8)
	s_waitcnt lgkmcnt(0)
	s_barrier
	v_mfma_f32_16x16x32_bf16 v[60:63], v[128:131], v[184:187], v[60:63]
	v_mfma_f32_16x16x32_bf16 v[56:59], v[136:139], v[184:187], v[56:59]
	v_mfma_f32_16x16x32_bf16 v[52:55], v[128:131], v[192:195], v[52:55]
	v_mfma_f32_16x16x32_bf16 v[48:51], v[136:139], v[192:195], v[48:51]
	v_mfma_f32_16x16x32_bf16 v[36:39], v[128:131], v[200:203], v[36:39]
	v_mfma_f32_16x16x32_bf16 v[32:35], v[136:139], v[200:203], v[32:35]
	v_mfma_f32_16x16x32_bf16 v[20:23], v[128:131], v[212:215], v[20:23]
	v_mfma_f32_16x16x32_bf16 v[16:19], v[136:139], v[212:215], v[16:19]
	v_mfma_f32_16x16x32_bf16 v[60:63], v[132:135], v[188:191], v[60:63]
	v_mfma_f32_16x16x32_bf16 v[56:59], v[140:143], v[188:191], v[56:59]
	v_mfma_f32_16x16x32_bf16 v[52:55], v[132:135], v[196:199], v[52:55]
	v_mfma_f32_16x16x32_bf16 v[48:51], v[140:143], v[196:199], v[48:51]
	v_mfma_f32_16x16x32_bf16 v[36:39], v[132:135], v[208:211], v[36:39]
	v_mfma_f32_16x16x32_bf16 v[32:35], v[140:143], v[208:211], v[32:35]
	v_mfma_f32_16x16x32_bf16 v[20:23], v[132:135], v[216:219], v[20:23]
	v_mfma_f32_16x16x32_bf16 v[16:19], v[140:143], v[216:219], v[16:19]
	v_mfma_f32_16x16x32_bf16 v[44:47], v[144:147], v[184:187], v[44:47]
	v_mfma_f32_16x16x32_bf16 v[40:43], v[168:171], v[184:187], v[40:43]
	v_mfma_f32_16x16x32_bf16 v[28:31], v[144:147], v[192:195], v[28:31]
	v_mfma_f32_16x16x32_bf16 v[24:27], v[168:171], v[192:195], v[24:27]
	v_mfma_f32_16x16x32_bf16 v[12:15], v[144:147], v[200:203], v[12:15]
	v_mfma_f32_16x16x32_bf16 v[8:11], v[168:171], v[200:203], v[8:11]
	v_mfma_f32_16x16x32_bf16 v[4:7], v[144:147], v[212:215], v[4:7]
	v_mfma_f32_16x16x32_bf16 v[0:3], v[168:171], v[212:215], v[0:3]
	v_mfma_f32_16x16x32_bf16 v[44:47], v[164:167], v[188:191], v[44:47]
	v_mfma_f32_16x16x32_bf16 v[40:43], v[172:175], v[188:191], v[40:43]
	v_mfma_f32_16x16x32_bf16 v[28:31], v[164:167], v[196:199], v[28:31]
	v_mfma_f32_16x16x32_bf16 v[24:27], v[172:175], v[196:199], v[24:27]
	v_mfma_f32_16x16x32_bf16 v[12:15], v[164:167], v[208:211], v[12:15]
	v_mfma_f32_16x16x32_bf16 v[8:11], v[172:175], v[208:211], v[8:11]
	v_mfma_f32_16x16x32_bf16 v[4:7], v[164:167], v[216:219], v[4:7]
	v_mfma_f32_16x16x32_bf16 v[0:3], v[172:175], v[216:219], v[0:3]
	s_barrier
	s_add_i32 s17, s17, 2
	s_add_u32 s4, s4, 0x100
	s_addc_u32 s5, s5, 0
	s_add_u32 s15, s15, 0x100
	s_addc_u32 s16, s16, 0
	s_cmp_gt_u32 s17, 29
	s_cbranch_scc0 .LBB0_96
	v_readlane_b32 s4, v249, 25
	v_readlane_b32 s5, v249, 26
	s_and_b64 vcc, exec, s[4:5]
	s_cbranch_vccz .LBB0_99
	s_barrier

; #define PG8_STAGE(bufoff, gbase, voff) do { _Pragma("unroll") for (int _i = 0; _i < 2; ++_i) \
;         __builtin_amdgcn_global_load_lds((const unsigned*)((const char*)(gbase) + (voff)[_i]), (LAS unsigned*)(lds + (bufoff) + ldsw + _i * 8192), 16, 0, 0); } while (0)
; #define PG8_LDA(dst, b, h) do { _Pragma("unroll") for (int m = 0; m < 4; ++m) _Pragma("unroll") for (int k = 0; k < 2; ++k) dst[m][k] = *(const LAS bf16x8*)(lds + PG8_SA(b, h) + aoff + m * 2048 + k * 1024); } while (0)
; #define PG8_LDB(dst, b, h) do { _Pragma("unroll") for (int n = 0; n < 2; ++n) _Pragma("unroll") for (int k = 0; k < 2; ++k) dst[n][k] = *(const LAS bf16x8*)(lds + PG8_SB(b, h) + boff + n * 2048 + k * 1024); } while (0)
; #define PG8_MMA(ai, bj, At, Bt) do { __builtin_amdgcn_s_setprio(1); _Pragma("unroll") for (int m = 0; m < 4; ++m) _Pragma("unroll") for (int n = 0; n < 2; ++n) _Pragma("unroll") for (int k = 0; k < 2; ++k) \
;         acc[ai][bj][m][n] = __builtin_amdgcn_mfma_f32_16x16x32_bf16(Bt[n][k], At[m][k], acc[ai][bj][m][n], 0, 0, 0); __builtin_amdgcn_s_setprio(0); } while (0)
; #define PG8_WAIT_V(n) asm volatile("s_waitcnt vmcnt(" #n ")" ::: "memory")
; #define PG8_WAIT_L(n) asm volatile("s_waitcnt lgkmcnt(" #n ")" ::: "memory")
; #define PG8_BAR __builtin_amdgcn_s_barrier()
; #define PG8_SCHED __builtin_amdgcn_sched_barrier(0)
;     DI void a_ready(const Unit& u) const { if (ctr && u.pm >= 128) wait_counter(ctr, target); }
; template <class Epi, class Sched>
; DI void gemm_phase(LAS unsigned char* lds, const int K, const Sched& S, const Epi& E, const int wid) {
;     ...
;         for (int t = 0; t < nt; t += 2) {
;             const bool last = (t == nt - 2);
;             const char* a1 = cA + (size_t)(t + 1) * kstep;
;             const char* a2 = last ? nA : cA + (size_t)(t + 2) * kstep; const char* b2 = last ? nB : cB + (size_t)(t + 2) * kstep;
;             const char* a3 = a2 + kstep; const char* b3 = b2 + kstep;
;             if (last && has_next) S.a_ready(nxt);
;             PG8_LDB(B0, 0, 0); PG8_LDB(B1, 0, 1); PG8_SCHED; PG8_LDA(At, 0, 0); PG8_STAGE(PG8_SA(1, 1), a1 + hstep, voffA);
;             PG8_WAIT_V(8); PG8_WAIT_L(0); PG8_BAR; PG8_MMA(0, 0, At, B0); PG8_MMA(0, 1, At, B1); PG8_BAR; PG8_SCHED;
;             PG8_LDA(At, 0, 1); PG8_STAGE(PG8_SB(0, 0), b2, voffB); PG8_STAGE(PG8_SB(0, 1), b2 + hstep, voffB); PG8_STAGE(PG8_SA(0, 0), a2, voffA);
.LBB0_539:
	ds_read_b128 v[128:131], v208
	ds_read_b128 v[132:135], v208 offset:1024
	ds_read_b128 v[136:139], v208 offset:2048
	ds_read_b128 v[140:143], v208 offset:3072
	ds_read_b128 v[144:147], v209
	ds_read_b128 v[148:151], v209 offset:1024
	ds_read_b128 v[152:155], v209 offset:2048
	ds_read_b128 v[156:159], v209 offset:3072
	s_add_i32 s49, s4, 2
	s_add_u32 s0, s56, 0xfffc0080
	s_addc_u32 s1, s57, -1
	s_cmp_eq_u32 s30, s4
	s_cselect_b32 s4, s52, s45
	s_cselect_b32 s7, s51, s1
	s_cselect_b32 s6, s50, s0
	s_cselect_b32 s5, s53, s47
	s_add_i32 s89, s85, 0xc000
	v_lshl_add_u64 v[212:213], s[56:57], 0, v[184:185]
	s_mov_b32 m0, s89
	s_add_i32 s26, s85, 0xe000
	ds_read_b128 v[160:163], v210
	ds_read_b128 v[164:167], v210 offset:1024
	ds_read_b128 v[168:171], v210 offset:2048
	ds_read_b128 v[172:175], v210 offset:3072
	ds_read_b128 v[188:191], v210 offset:4096
	ds_read_b128 v[192:195], v210 offset:5120
	ds_read_b128 v[196:199], v210 offset:6144
	ds_read_b128 v[200:203], v210 offset:7168
	global_load_lds_dwordx4 v[212:213], off
	v_lshl_add_u64 v[212:213], s[56:57], 0, v[186:187]
	s_mov_b32 m0, s26
	s_nop 0
	global_load_lds_dwordx4 v[212:213], off
	s_waitcnt vmcnt(8)
	s_waitcnt lgkmcnt(0)
	s_barrier
	v_mfma_f32_16x16x32_bf16 v[124:127], v[128:131], v[160:163], v[124:127]
	v_mfma_f32_16x16x32_bf16 v[120:123], v[136:139], v[160:163], v[120:123]
	v_mfma_f32_16x16x32_bf16 v[108:111], v[128:131], v[168:171], v[108:111]
	v_mfma_f32_16x16x32_bf16 v[104:107], v[136:139], v[168:171], v[104:107]
	v_mfma_f32_16x16x32_bf16 v[96:99], v[128:131], v[188:191], v[96:99]
	v_mfma_f32_16x16x32_bf16 v[88:91], v[136:139], v[188:191], v[88:91]
	v_mfma_f32_16x16x32_bf16 v[80:83], v[128:131], v[196:199], v[80:83]
	v_mfma_f32_16x16x32_bf16 v[72:75], v[136:139], v[196:199], v[72:75]
	v_mfma_f32_16x16x32_bf16 v[124:127], v[132:135], v[164:167], v[124:127]
	v_mfma_f32_16x16x32_bf16 v[120:123], v[140:143], v[164:167], v[120:123]
	v_mfma_f32_16x16x32_bf16 v[108:111], v[132:135], v[172:175], v[108:111]
	v_mfma_f32_16x16x32_bf16 v[104:107], v[140:143], v[172:175], v[104:107]
	v_mfma_f32_16x16x32_bf16 v[96:99], v[132:135], v[192:195], v[96:99]
	v_mfma_f32_16x16x32_bf16 v[88:91], v[140:143], v[192:195], v[88:91]
	v_mfma_f32_16x16x32_bf16 v[80:83], v[132:135], v[200:203], v[80:83]
	v_mfma_f32_16x16x32_bf16 v[72:75], v[140:143], v[200:203], v[72:75]
	v_mfma_f32_16x16x32_bf16 v[116:119], v[144:147], v[160:163], v[116:119]
	v_mfma_f32_16x16x32_bf16 v[112:115], v[152:155], v[160:163], v[112:115]
	v_mfma_f32_16x16x32_bf16 v[100:103], v[144:147], v[168:171], v[100:103]
	v_mfma_f32_16x16x32_bf16 v[92:95], v[152:155], v[168:171], v[92:95]
	v_mfma_f32_16x16x32_bf16 v[84:87], v[144:147], v[188:191], v[84:87]
	v_mfma_f32_16x16x32_bf16 v[76:79], v[152:155], v[188:191], v[76:79]
	v_mfma_f32_16x16x32_bf16 v[68:71], v[144:147], v[196:199], v[68:71]
	v_mfma_f32_16x16x32_bf16 v[64:67], v[152:155], v[196:199], v[64:67]
	v_mfma_f32_16x16x32_bf16 v[116:119], v[148:151], v[164:167], v[116:119]
	v_mfma_f32_16x16x32_bf16 v[112:115], v[156:159], v[164:167], v[112:115]
	v_mfma_f32_16x16x32_bf16 v[100:103], v[148:151], v[172:175], v[100:103]
	v_mfma_f32_16x16x32_bf16 v[92:95], v[156:159], v[172:175], v[92:95]
	v_mfma_f32_16x16x32_bf16 v[84:87], v[148:151], v[192:195], v[84:87]
	v_mfma_f32_16x16x32_bf16 v[76:79], v[156:159], v[192:195], v[76:79]
	v_mfma_f32_16x16x32_bf16 v[68:71], v[148:151], v[200:203], v[68:71]
	v_mfma_f32_16x16x32_bf16 v[64:67], v[156:159], v[200:203], v[64:67]
	s_barrier
	s_add_i32 s27, s70, s95
	s_add_i32 s22, s27, 0x2000
	v_lshl_add_u64 v[212:213], s[4:5], 0, v[178:179]
	s_mov_b32 m0, s27
	s_add_u32 s0, s4, 0x40000
	ds_read_b128 v[160:163], v210 offset:16384
	ds_read_b128 v[164:167], v210 offset:17408
	ds_read_b128 v[168:171], v210 offset:18432
	ds_read_b128 v[172:175], v210 offset:19456
	ds_read_b128 v[188:191], v210 offset:20480
	ds_read_b128 v[192:195], v210 offset:21504
	ds_read_b128 v[196:199], v210 offset:22528
	ds_read_b128 v[200:203], v210 offset:23552
	global_load_lds_dwordx4 v[212:213], off
	v_lshl_add_u64 v[214:215], s[4:5], 0, v[182:183]
	s_mov_b32 m0, s22
	s_addc_u32 s1, s5, 0
	s_add_i32 s23, s2, s95
	global_load_lds_dwordx4 v[214:215], off
	v_lshl_add_u64 v[216:217], s[0:1], 0, v[178:179]
	s_mov_b32 m0, s23
	s_add_i32 s87, s23, 0x2000
	global_load_lds_dwordx4 v[216:217], off
	v_lshl_add_u64 v[216:217], s[0:1], 0, v[182:183]
	s_mov_b32 m0, s87
	v_lshl_add_u64 v[218:219], s[6:7], 0, v[180:181]
	global_load_lds_dwordx4 v[216:217], off
	v_lshl_add_u64 v[216:217], s[6:7], 0, v[176:177]
	s_mov_b32 m0, s85
	s_nop 0
	global_load_lds_dwordx4 v[216:217], off
	s_mov_b32 m0, s33
	s_nop 0
	global_load_lds_dwordx4 v[218:219], off
	s_waitcnt vmcnt(8)
	s_waitcnt lgkmcnt(0)
	s_barrier
; #define PG8_STAGE(bufoff, gbase, voff) do { _Pragma("unroll") for (int _i = 0; _i < 2; ++_i) \
;         __builtin_amdgcn_global_load_lds((const unsigned*)((const char*)(gbase) + (voff)[_i]), (LAS unsigned*)(lds + (bufoff) + ldsw + _i * 8192), 16, 0, 0); } while (0)
; #define PG8_LDA(dst, b, h) do { _Pragma("unroll") for (int m = 0; m < 4; ++m) _Pragma("unroll") for (int k = 0; k < 2; ++k) dst[m][k] = *(const LAS bf16x8*)(lds + PG8_SA(b, h) + aoff + m * 2048 + k * 1024); } while (0)
; #define PG8_LDB(dst, b, h) do { _Pragma("unroll") for (int n = 0; n < 2; ++n) _Pragma("unroll") for (int k = 0; k < 2; ++k) dst[n][k] = *(const LAS bf16x8*)(lds + PG8_SB(b, h) + boff + n * 2048 + k * 1024); } while (0)
; #define PG8_MMA(ai, bj, At, Bt) do { __builtin_amdgcn_s_setprio(1); _Pragma("unroll") for (int m = 0; m < 4; ++m) _Pragma("unroll") for (int n = 0; n < 2; ++n) _Pragma("unroll") for (int k = 0; k < 2; ++k) \
;         acc[ai][bj][m][n] = __builtin_amdgcn_mfma_f32_16x16x32_bf16(Bt[n][k], At[m][k], acc[ai][bj][m][n], 0, 0, 0); __builtin_amdgcn_s_setprio(0); } while (0)
; #define PG8_WAIT_V(n) asm volatile("s_waitcnt vmcnt(" #n ")" ::: "memory")
; #define PG8_WAIT_L(n) asm volatile("s_waitcnt lgkmcnt(" #n ")" ::: "memory")
; #define PG8_BAR __builtin_amdgcn_s_barrier()
; #define PG8_SCHED __builtin_amdgcn_sched_barrier(0)
; template <class Epi, class Sched>
; DI void gemm_phase(LAS unsigned char* lds, const int K, const Sched& S, const Epi& E, const int wid) {
;     ...
;             PG8_WAIT_V(8); PG8_WAIT_L(0); PG8_BAR; PG8_MMA(1, 0, At, B0); PG8_MMA(1, 1, At, B1); PG8_BAR; PG8_SCHED;
;             PG8_LDB(B0, 1, 0); PG8_LDB(B1, 1, 1); PG8_SCHED; PG8_LDA(At, 1, 0); PG8_STAGE(PG8_SA(0, 1), a2 + hstep, voffA);
;             PG8_WAIT_V(8); PG8_WAIT_L(0); PG8_BAR; PG8_MMA(0, 0, At, B0); PG8_MMA(0, 1, At, B1); PG8_BAR; PG8_SCHED;
	v_mfma_f32_16x16x32_bf16 v[60:63], v[128:131], v[160:163], v[60:63]
	v_mfma_f32_16x16x32_bf16 v[56:59], v[136:139], v[160:163], v[56:59]
	v_mfma_f32_16x16x32_bf16 v[48:51], v[128:131], v[168:171], v[48:51]
	v_mfma_f32_16x16x32_bf16 v[40:43], v[136:139], v[168:171], v[40:43]
	v_mfma_f32_16x16x32_bf16 v[32:35], v[128:131], v[188:191], v[32:35]
	v_mfma_f32_16x16x32_bf16 v[24:27], v[136:139], v[188:191], v[24:27]
	v_mfma_f32_16x16x32_bf16 v[16:19], v[128:131], v[196:199], v[16:19]
	v_mfma_f32_16x16x32_bf16 v[8:11], v[136:139], v[196:199], v[8:11]
	v_mfma_f32_16x16x32_bf16 v[60:63], v[132:135], v[164:167], v[60:63]
	v_mfma_f32_16x16x32_bf16 v[56:59], v[140:143], v[164:167], v[56:59]
	v_mfma_f32_16x16x32_bf16 v[48:51], v[132:135], v[172:175], v[48:51]
	v_mfma_f32_16x16x32_bf16 v[40:43], v[140:143], v[172:175], v[40:43]
	v_mfma_f32_16x16x32_bf16 v[32:35], v[132:135], v[192:195], v[32:35]
	v_mfma_f32_16x16x32_bf16 v[24:27], v[140:143], v[192:195], v[24:27]
	v_mfma_f32_16x16x32_bf16 v[16:19], v[132:135], v[200:203], v[16:19]
	v_mfma_f32_16x16x32_bf16 v[8:11], v[140:143], v[200:203], v[8:11]
	v_mfma_f32_16x16x32_bf16 v[52:55], v[144:147], v[160:163], v[52:55]
	v_mfma_f32_16x16x32_bf16 v[44:47], v[152:155], v[160:163], v[44:47]
	v_mfma_f32_16x16x32_bf16 v[36:39], v[144:147], v[168:171], v[36:39]
	v_mfma_f32_16x16x32_bf16 v[28:31], v[152:155], v[168:171], v[28:31]
	v_mfma_f32_16x16x32_bf16 v[20:23], v[144:147], v[188:191], v[20:23]
	v_mfma_f32_16x16x32_bf16 v[12:15], v[152:155], v[188:191], v[12:15]
	v_mfma_f32_16x16x32_bf16 v[4:7], v[144:147], v[196:199], v[4:7]
	v_mfma_f32_16x16x32_bf16 v[0:3], v[152:155], v[196:199], v[0:3]
	v_mfma_f32_16x16x32_bf16 v[52:55], v[148:151], v[164:167], v[52:55]
	v_mfma_f32_16x16x32_bf16 v[44:47], v[156:159], v[164:167], v[44:47]
	v_mfma_f32_16x16x32_bf16 v[36:39], v[148:151], v[172:175], v[36:39]
	v_mfma_f32_16x16x32_bf16 v[28:31], v[156:159], v[172:175], v[28:31]
	v_mfma_f32_16x16x32_bf16 v[20:23], v[148:151], v[192:195], v[20:23]
	v_mfma_f32_16x16x32_bf16 v[12:15], v[156:159], v[192:195], v[12:15]
	v_mfma_f32_16x16x32_bf16 v[4:7], v[148:151], v[200:203], v[4:7]
	v_mfma_f32_16x16x32_bf16 v[0:3], v[156:159], v[200:203], v[0:3]
	s_barrier
	s_add_i32 s96, 0, 0x18000
	s_add_i32 s90, 0, 0x1c000
	v_add_u32_e32 v140, s96, v207
	v_add_u32_e32 v156, s90, v207
	ds_read_b128 v[128:131], v140
	ds_read_b128 v[132:135], v140 offset:1024
	ds_read_b128 v[136:139], v140 offset:2048
	ds_read_b128 v[140:143], v140 offset:3072
	ds_read_b128 v[144:147], v156
	ds_read_b128 v[148:151], v156 offset:1024
	ds_read_b128 v[152:155], v156 offset:2048
	ds_read_b128 v[156:159], v156 offset:3072
	s_add_u32 s6, s6, 0x40000
	s_addc_u32 s7, s7, 0
	s_mov_b32 m0, s29
	v_lshl_add_u64 v[220:221], s[6:7], 0, v[176:177]
	ds_read_b128 v[160:163], v210 offset:32768
	ds_read_b128 v[164:167], v210 offset:33792
	ds_read_b128 v[168:171], v210 offset:34816
	ds_read_b128 v[172:175], v210 offset:35840
	ds_read_b128 v[188:191], v210 offset:36864
	ds_read_b128 v[192:195], v210 offset:37888
	ds_read_b128 v[196:199], v210 offset:38912
	ds_read_b128 v[200:203], v210 offset:39936
	global_load_lds_dwordx4 v[220:221], off
	v_lshl_add_u64 v[220:221], s[6:7], 0, v[180:181]
	s_mov_b32 m0, s97
	s_nop 0
	global_load_lds_dwordx4 v[220:221], off
	s_waitcnt vmcnt(8)
	s_waitcnt lgkmcnt(0)
	s_barrier
	v_mfma_f32_16x16x32_bf16 v[124:127], v[128:131], v[160:163], v[124:127]
	v_mfma_f32_16x16x32_bf16 v[120:123], v[136:139], v[160:163], v[120:123]
	v_mfma_f32_16x16x32_bf16 v[108:111], v[128:131], v[168:171], v[108:111]
	v_mfma_f32_16x16x32_bf16 v[104:107], v[136:139], v[168:171], v[104:107]
	v_mfma_f32_16x16x32_bf16 v[96:99], v[128:131], v[188:191], v[96:99]
	v_mfma_f32_16x16x32_bf16 v[88:91], v[136:139], v[188:191], v[88:91]
	v_mfma_f32_16x16x32_bf16 v[80:83], v[128:131], v[196:199], v[80:83]
	v_mfma_f32_16x16x32_bf16 v[72:75], v[136:139], v[196:199], v[72:75]
	v_mfma_f32_16x16x32_bf16 v[124:127], v[132:135], v[164:167], v[124:127]
	v_mfma_f32_16x16x32_bf16 v[120:123], v[140:143], v[164:167], v[120:123]
	v_mfma_f32_16x16x32_bf16 v[108:111], v[132:135], v[172:175], v[108:111]
	v_mfma_f32_16x16x32_bf16 v[104:107], v[140:143], v[172:175], v[104:107]
	v_mfma_f32_16x16x32_bf16 v[96:99], v[132:135], v[192:195], v[96:99]
	v_mfma_f32_16x16x32_bf16 v[88:91], v[140:143], v[192:195], v[88:91]
	v_mfma_f32_16x16x32_bf16 v[80:83], v[132:135], v[200:203], v[80:83]
	v_mfma_f32_16x16x32_bf16 v[72:75], v[140:143], v[200:203], v[72:75]
	v_mfma_f32_16x16x32_bf16 v[116:119], v[144:147], v[160:163], v[116:119]
	v_mfma_f32_16x16x32_bf16 v[112:115], v[152:155], v[160:163], v[112:115]
	v_mfma_f32_16x16x32_bf16 v[100:103], v[144:147], v[168:171], v[100:103]
	v_mfma_f32_16x16x32_bf16 v[92:95], v[152:155], v[168:171], v[92:95]
	v_mfma_f32_16x16x32_bf16 v[84:87], v[144:147], v[188:191], v[84:87]
	v_mfma_f32_16x16x32_bf16 v[76:79], v[152:155], v[188:191], v[76:79]
	v_mfma_f32_16x16x32_bf16 v[68:71], v[144:147], v[196:199], v[68:71]
	v_mfma_f32_16x16x32_bf16 v[64:67], v[152:155], v[196:199], v[64:67]
	v_mfma_f32_16x16x32_bf16 v[116:119], v[148:151], v[164:167], v[116:119]
	v_mfma_f32_16x16x32_bf16 v[112:115], v[156:159], v[164:167], v[112:115]
	v_mfma_f32_16x16x32_bf16 v[100:103], v[148:151], v[172:175], v[100:103]
	v_mfma_f32_16x16x32_bf16 v[92:95], v[156:159], v[172:175], v[92:95]
	v_mfma_f32_16x16x32_bf16 v[84:87], v[148:151], v[192:195], v[84:87]
	v_mfma_f32_16x16x32_bf16 v[76:79], v[156:159], v[192:195], v[76:79]
	v_mfma_f32_16x16x32_bf16 v[68:71], v[148:151], v[200:203], v[68:71]
	v_mfma_f32_16x16x32_bf16 v[64:67], v[156:159], v[200:203], v[64:67]
	s_barrier
; #define PG8_STAGE(bufoff, gbase, voff) do { _Pragma("unroll") for (int _i = 0; _i < 2; ++_i) \
;         __builtin_amdgcn_global_load_lds((const unsigned*)((const char*)(gbase) + (voff)[_i]), (LAS unsigned*)(lds + (bufoff) + ldsw + _i * 8192), 16, 0, 0); } while (0)
; #define PG8_LDA(dst, b, h) do { _Pragma("unroll") for (int m = 0; m < 4; ++m) _Pragma("unroll") for (int k = 0; k < 2; ++k) dst[m][k] = *(const LAS bf16x8*)(lds + PG8_SA(b, h) + aoff + m * 2048 + k * 1024); } while (0)
; #define PG8_MMA(ai, bj, At, Bt) do { __builtin_amdgcn_s_setprio(1); _Pragma("unroll") for (int m = 0; m < 4; ++m) _Pragma("unroll") for (int n = 0; n < 2; ++n) _Pragma("unroll") for (int k = 0; k < 2; ++k) \
;         acc[ai][bj][m][n] = __builtin_amdgcn_mfma_f32_16x16x32_bf16(Bt[n][k], At[m][k], acc[ai][bj][m][n], 0, 0, 0); __builtin_amdgcn_s_setprio(0); } while (0)
; #define PG8_WAIT_V(n) asm volatile("s_waitcnt vmcnt(" #n ")" ::: "memory")
; #define PG8_WAIT_L(n) asm volatile("s_waitcnt lgkmcnt(" #n ")" ::: "memory")
; #define PG8_BAR __builtin_amdgcn_s_barrier()
; #define PG8_SCHED __builtin_amdgcn_sched_barrier(0)
; template <class Epi, class Sched>
; DI void gemm_phase(LAS unsigned char* lds, const int K, const Sched& S, const Epi& E, const int wid) {
;     ...
;             PG8_LDA(At, 1, 1); PG8_STAGE(PG8_SB(1, 0), b3, voffB); PG8_STAGE(PG8_SB(1, 1), b3 + hstep, voffB); PG8_STAGE(PG8_SA(1, 0), a3, voffA);
;             PG8_WAIT_V(8); PG8_WAIT_L(0); PG8_BAR; PG8_MMA(1, 0, At, B0); PG8_MMA(1, 1, At, B1); PG8_BAR; PG8_SCHED;
;         }
	s_add_i32 s94, s96, s95
	s_add_i32 s84, s94, 0x2000
	v_lshl_add_u64 v[212:213], v[212:213], 0, s[34:35]
	s_mov_b32 m0, s94
	s_add_u32 s4, s4, 0x40080
	ds_read_b128 v[160:163], v210 offset:49152
	ds_read_b128 v[164:167], v210 offset:50176
	ds_read_b128 v[168:171], v210 offset:51200
	ds_read_b128 v[172:175], v210 offset:52224
	ds_read_b128 v[188:191], v210 offset:53248
	ds_read_b128 v[192:195], v210 offset:54272
	ds_read_b128 v[196:199], v210 offset:55296
	ds_read_b128 v[200:203], v210 offset:56320
	global_load_lds_dwordx4 v[212:213], off
	v_lshl_add_u64 v[212:213], v[214:215], 0, s[34:35]
	s_mov_b32 m0, s84
	s_addc_u32 s5, s5, 0
	s_add_i32 s86, s90, s95
	global_load_lds_dwordx4 v[212:213], off
	v_lshl_add_u64 v[212:213], s[4:5], 0, v[178:179]
	s_mov_b32 m0, s86
	s_add_i32 s28, s86, 0x2000
	global_load_lds_dwordx4 v[212:213], off
	v_lshl_add_u64 v[212:213], s[4:5], 0, v[182:183]
	s_mov_b32 m0, s28
	s_nop 0
	global_load_lds_dwordx4 v[212:213], off
	v_lshl_add_u64 v[212:213], v[216:217], 0, s[34:35]
	s_mov_b32 m0, s91
	s_nop 0
	global_load_lds_dwordx4 v[212:213], off
	v_lshl_add_u64 v[212:213], v[218:219], 0, s[34:35]
	s_mov_b32 m0, s88
	s_nop 0
	global_load_lds_dwordx4 v[212:213], off
	s_waitcnt vmcnt(8)
	s_waitcnt lgkmcnt(0)
	s_barrier
	v_mfma_f32_16x16x32_bf16 v[60:63], v[128:131], v[160:163], v[60:63]
	v_mfma_f32_16x16x32_bf16 v[56:59], v[136:139], v[160:163], v[56:59]
	v_mfma_f32_16x16x32_bf16 v[48:51], v[128:131], v[168:171], v[48:51]
	v_mfma_f32_16x16x32_bf16 v[40:43], v[136:139], v[168:171], v[40:43]
	v_mfma_f32_16x16x32_bf16 v[32:35], v[128:131], v[188:191], v[32:35]
	v_mfma_f32_16x16x32_bf16 v[24:27], v[136:139], v[188:191], v[24:27]
	v_mfma_f32_16x16x32_bf16 v[16:19], v[128:131], v[196:199], v[16:19]
	v_mfma_f32_16x16x32_bf16 v[8:11], v[136:139], v[196:199], v[8:11]
	v_mfma_f32_16x16x32_bf16 v[60:63], v[132:135], v[164:167], v[60:63]
	v_mfma_f32_16x16x32_bf16 v[56:59], v[140:143], v[164:167], v[56:59]
	v_mfma_f32_16x16x32_bf16 v[48:51], v[132:135], v[172:175], v[48:51]
	v_mfma_f32_16x16x32_bf16 v[40:43], v[140:143], v[172:175], v[40:43]
	v_mfma_f32_16x16x32_bf16 v[32:35], v[132:135], v[192:195], v[32:35]
	v_mfma_f32_16x16x32_bf16 v[24:27], v[140:143], v[192:195], v[24:27]
	v_mfma_f32_16x16x32_bf16 v[16:19], v[132:135], v[200:203], v[16:19]
	v_mfma_f32_16x16x32_bf16 v[8:11], v[140:143], v[200:203], v[8:11]
	v_mfma_f32_16x16x32_bf16 v[52:55], v[144:147], v[160:163], v[52:55]
	v_mfma_f32_16x16x32_bf16 v[44:47], v[152:155], v[160:163], v[44:47]
	v_mfma_f32_16x16x32_bf16 v[36:39], v[144:147], v[168:171], v[36:39]
	v_mfma_f32_16x16x32_bf16 v[28:31], v[152:155], v[168:171], v[28:31]
	v_mfma_f32_16x16x32_bf16 v[20:23], v[144:147], v[188:191], v[20:23]
	v_mfma_f32_16x16x32_bf16 v[12:15], v[152:155], v[188:191], v[12:15]
	v_mfma_f32_16x16x32_bf16 v[4:7], v[144:147], v[196:199], v[4:7]
	v_mfma_f32_16x16x32_bf16 v[0:3], v[152:155], v[196:199], v[0:3]
	v_mfma_f32_16x16x32_bf16 v[52:55], v[148:151], v[164:167], v[52:55]
	v_mfma_f32_16x16x32_bf16 v[44:47], v[156:159], v[164:167], v[44:47]
	v_mfma_f32_16x16x32_bf16 v[36:39], v[148:151], v[172:175], v[36:39]
	v_mfma_f32_16x16x32_bf16 v[28:31], v[156:159], v[172:175], v[28:31]
	v_mfma_f32_16x16x32_bf16 v[20:23], v[148:151], v[192:195], v[20:23]
	v_mfma_f32_16x16x32_bf16 v[12:15], v[156:159], v[192:195], v[12:15]
	v_mfma_f32_16x16x32_bf16 v[4:7], v[148:151], v[200:203], v[4:7]
	v_mfma_f32_16x16x32_bf16 v[0:3], v[156:159], v[200:203], v[0:3]
	s_barrier
	s_add_u32 s56, s56, 0x100
	s_addc_u32 s57, s57, 0
	s_add_u32 s45, s45, 0x100
	s_addc_u32 s47, s47, 0
	s_cmp_ge_u32 s49, s43
	s_mov_b32 s4, s49
	s_cbranch_scc0 .LBB0_539
	v_readlane_b32 s4, v249, 25
	v_readlane_b32 s5, v249, 26
	s_and_b64 vcc, exec, s[4:5]
	s_cbranch_vccz .LBB0_542
	s_barrier

; #define PG8_STAGE(bufoff, gbase, voff) do { _Pragma("unroll") for (int _i = 0; _i < 2; ++_i) \
;         __builtin_amdgcn_global_load_lds((const unsigned*)((const char*)(gbase) + (voff)[_i]), (LAS unsigned*)(lds + (bufoff) + ldsw + _i * 8192), 16, 0, 0); } while (0)
; #define PG8_LDA(dst, b, h) do { _Pragma("unroll") for (int m = 0; m < 4; ++m) _Pragma("unroll") for (int k = 0; k < 2; ++k) dst[m][k] = *(const LAS bf16x8*)(lds + PG8_SA(b, h) + aoff + m * 2048 + k * 1024); } while (0)
; #define PG8_LDB(dst, b, h) do { _Pragma("unroll") for (int n = 0; n < 2; ++n) _Pragma("unroll") for (int k = 0; k < 2; ++k) dst[n][k] = *(const LAS bf16x8*)(lds + PG8_SB(b, h) + boff + n * 2048 + k * 1024); } while (0)
; #define PG8_MMA(ai, bj, At, Bt) do { __builtin_amdgcn_s_setprio(1); _Pragma("unroll") for (int m = 0; m < 4; ++m) _Pragma("unroll") for (int n = 0; n < 2; ++n) _Pragma("unroll") for (int k = 0; k < 2; ++k) \
;         acc[ai][bj][m][n] = __builtin_amdgcn_mfma_f32_16x16x32_bf16(Bt[n][k], At[m][k], acc[ai][bj][m][n], 0, 0, 0); __builtin_amdgcn_s_setprio(0); } while (0)
; #define PG8_WAIT_V(n) asm volatile("s_waitcnt vmcnt(" #n ")" ::: "memory")
; #define PG8_WAIT_L(n) asm volatile("s_waitcnt lgkmcnt(" #n ")" ::: "memory")
; #define PG8_BAR __builtin_amdgcn_s_barrier()
; #define PG8_SCHED __builtin_amdgcn_sched_barrier(0)
; template <class Epi, class Sched>
; DI void gemm_phase(LAS unsigned char* lds, const int K, const Sched& S, const Epi& E, const int wid) {
;     ...
;             const bool last = (t == nt - 2);
;             const char* a1 = cA + (size_t)(t + 1) * kstep;
;             const char* a2 = last ? nA : cA + (size_t)(t + 2) * kstep; const char* b2 = last ? nB : cB + (size_t)(t + 2) * kstep;
;             const char* a3 = a2 + kstep; const char* b3 = b2 + kstep;
;             if (last && has_next) S.a_ready(nxt);
;             PG8_LDB(B0, 0, 0); PG8_LDB(B1, 0, 1); PG8_SCHED; PG8_LDA(At, 0, 0); PG8_STAGE(PG8_SA(1, 1), a1 + hstep, voffA);
;             PG8_WAIT_V(8); PG8_WAIT_L(0); PG8_BAR; PG8_MMA(0, 0, At, B0); PG8_MMA(0, 1, At, B1); PG8_BAR; PG8_SCHED;
;             PG8_LDA(At, 0, 1); PG8_STAGE(PG8_SB(0, 0), b2, voffB); PG8_STAGE(PG8_SB(0, 1), b2 + hstep, voffB); PG8_STAGE(PG8_SA(0, 0), a2, voffA);
;             PG8_WAIT_V(8); PG8_WAIT_L(0); PG8_BAR; PG8_MMA(1, 0, At, B0); PG8_MMA(1, 1, At, B1); PG8_BAR; PG8_SCHED;
.LBB0_706:
	s_or_b32 s44, s6, 1
	s_lshl_b64 s[20:21], s[44:45], 7
	s_add_u32 s15, s62, s20
	s_addc_u32 s24, s63, s21
	s_add_i32 s44, s6, 2
	v_add_u32_e32 v140, s70, v208
	v_add_u32_e32 v156, s2, v208
	s_lshl_b64 s[20:21], s[44:45], 7
	s_waitcnt lgkmcnt(0)
	ds_read_b128 v[128:131], v140
	ds_read_b128 v[132:135], v140 offset:1024
	ds_read_b128 v[136:139], v140 offset:2048
	ds_read_b128 v[140:143], v140 offset:3072
	ds_read_b128 v[144:147], v156
	ds_read_b128 v[148:151], v156 offset:1024
	ds_read_b128 v[152:155], v156 offset:2048
	ds_read_b128 v[156:159], v156 offset:3072
	s_add_u32 s25, s62, s20
	s_addc_u32 s39, s63, s21
	s_and_b64 s[6:7], s[4:5], exec
	s_cselect_b32 s7, s53, s39
	s_cselect_b32 s6, s52, s25
	s_add_u32 s20, s60, s20
	s_addc_u32 s21, s61, s21
	s_and_b64 s[4:5], s[4:5], exec
	s_cselect_b32 s5, s55, s21
	s_cselect_b32 s4, s54, s20
	s_add_u32 s20, s15, 0x80000
	s_addc_u32 s21, s24, 0
	s_mov_b32 m0, s89
	v_lshl_add_u64 v[200:201], s[20:21], 0, v[184:185]
	ds_read_b128 v[160:163], v210
	ds_read_b128 v[164:167], v210 offset:1024
	ds_read_b128 v[168:171], v210 offset:2048
	ds_read_b128 v[172:175], v210 offset:3072
	ds_read_b128 v[176:179], v210 offset:4096
	ds_read_b128 v[180:183], v210 offset:5120
	ds_read_b128 v[192:195], v210 offset:6144
	ds_read_b128 v[196:199], v210 offset:7168
	global_load_lds_dwordx4 v[200:201], off
	v_lshl_add_u64 v[200:201], s[20:21], 0, v[188:189]
	s_mov_b32 m0, s26
	s_nop 0
	global_load_lds_dwordx4 v[200:201], off
	s_waitcnt vmcnt(8)
	s_waitcnt lgkmcnt(0)
	s_barrier
	v_mfma_f32_16x16x32_bf16 v[124:127], v[128:131], v[160:163], v[124:127]
	v_mfma_f32_16x16x32_bf16 v[120:123], v[136:139], v[160:163], v[120:123]
	v_mfma_f32_16x16x32_bf16 v[116:119], v[128:131], v[168:171], v[116:119]
	v_mfma_f32_16x16x32_bf16 v[112:115], v[136:139], v[168:171], v[112:115]
	v_mfma_f32_16x16x32_bf16 v[100:103], v[128:131], v[176:179], v[100:103]
	v_mfma_f32_16x16x32_bf16 v[96:99], v[136:139], v[176:179], v[96:99]
	v_mfma_f32_16x16x32_bf16 v[84:87], v[128:131], v[192:195], v[84:87]
	v_mfma_f32_16x16x32_bf16 v[80:83], v[136:139], v[192:195], v[80:83]
	v_mfma_f32_16x16x32_bf16 v[124:127], v[132:135], v[164:167], v[124:127]
	v_mfma_f32_16x16x32_bf16 v[120:123], v[140:143], v[164:167], v[120:123]
	v_mfma_f32_16x16x32_bf16 v[116:119], v[132:135], v[172:175], v[116:119]
	v_mfma_f32_16x16x32_bf16 v[112:115], v[140:143], v[172:175], v[112:115]
	v_mfma_f32_16x16x32_bf16 v[100:103], v[132:135], v[180:183], v[100:103]
	v_mfma_f32_16x16x32_bf16 v[96:99], v[140:143], v[180:183], v[96:99]
	v_mfma_f32_16x16x32_bf16 v[84:87], v[132:135], v[196:199], v[84:87]
	v_mfma_f32_16x16x32_bf16 v[80:83], v[140:143], v[196:199], v[80:83]
	v_mfma_f32_16x16x32_bf16 v[108:111], v[144:147], v[160:163], v[108:111]
	v_mfma_f32_16x16x32_bf16 v[104:107], v[152:155], v[160:163], v[104:107]
	v_mfma_f32_16x16x32_bf16 v[92:95], v[144:147], v[168:171], v[92:95]
	v_mfma_f32_16x16x32_bf16 v[88:91], v[152:155], v[168:171], v[88:91]
	v_mfma_f32_16x16x32_bf16 v[76:79], v[144:147], v[176:179], v[76:79]
	v_mfma_f32_16x16x32_bf16 v[72:75], v[152:155], v[176:179], v[72:75]
	v_mfma_f32_16x16x32_bf16 v[68:71], v[144:147], v[192:195], v[68:71]
	v_mfma_f32_16x16x32_bf16 v[64:67], v[152:155], v[192:195], v[64:67]
	v_mfma_f32_16x16x32_bf16 v[108:111], v[148:151], v[164:167], v[108:111]
	v_mfma_f32_16x16x32_bf16 v[104:107], v[156:159], v[164:167], v[104:107]
	v_mfma_f32_16x16x32_bf16 v[92:95], v[148:151], v[172:175], v[92:95]
	v_mfma_f32_16x16x32_bf16 v[88:91], v[156:159], v[172:175], v[88:91]
	v_mfma_f32_16x16x32_bf16 v[76:79], v[148:151], v[180:183], v[76:79]
	v_mfma_f32_16x16x32_bf16 v[72:75], v[156:159], v[180:183], v[72:75]
	v_mfma_f32_16x16x32_bf16 v[68:71], v[148:151], v[196:199], v[68:71]
	v_mfma_f32_16x16x32_bf16 v[64:67], v[156:159], v[196:199], v[64:67]
	s_barrier
	s_mov_b32 m0, s27
	v_lshl_add_u64 v[200:201], s[4:5], 0, v[186:187]
	s_add_u32 s20, s4, 0x80000
	ds_read_b128 v[160:163], v210 offset:16384
	ds_read_b128 v[164:167], v210 offset:17408
	ds_read_b128 v[168:171], v210 offset:18432
	ds_read_b128 v[172:175], v210 offset:19456
	ds_read_b128 v[176:179], v210 offset:20480
	ds_read_b128 v[180:183], v210 offset:21504
	ds_read_b128 v[192:195], v210 offset:22528
	ds_read_b128 v[196:199], v210 offset:23552
	global_load_lds_dwordx4 v[200:201], off
	v_lshl_add_u64 v[202:203], s[4:5], 0, v[190:191]
	s_mov_b32 m0, s22
	s_addc_u32 s21, s5, 0
	global_load_lds_dwordx4 v[202:203], off
	v_lshl_add_u64 v[204:205], s[20:21], 0, v[186:187]
	s_mov_b32 m0, s23
	v_lshl_add_u64 v[212:213], s[6:7], 0, v[188:189]
	global_load_lds_dwordx4 v[204:205], off
	v_lshl_add_u64 v[204:205], s[20:21], 0, v[190:191]
	s_mov_b32 m0, s87
	s_nop 0
	global_load_lds_dwordx4 v[204:205], off
	v_lshl_add_u64 v[204:205], s[6:7], 0, v[184:185]
	s_mov_b32 m0, s85
	s_nop 0
	global_load_lds_dwordx4 v[204:205], off
	s_mov_b32 m0, s33
	s_nop 0
	global_load_lds_dwordx4 v[212:213], off
	s_waitcnt vmcnt(8)
	s_waitcnt lgkmcnt(0)
	s_barrier
; #define PG8_STAGE(bufoff, gbase, voff) do { _Pragma("unroll") for (int _i = 0; _i < 2; ++_i) \
;         __builtin_amdgcn_global_load_lds((const unsigned*)((const char*)(gbase) + (voff)[_i]), (LAS unsigned*)(lds + (bufoff) + ldsw + _i * 8192), 16, 0, 0); } while (0)
; #define PG8_LDA(dst, b, h) do { _Pragma("unroll") for (int m = 0; m < 4; ++m) _Pragma("unroll") for (int k = 0; k < 2; ++k) dst[m][k] = *(const LAS bf16x8*)(lds + PG8_SA(b, h) + aoff + m * 2048 + k * 1024); } while (0)
; #define PG8_LDB(dst, b, h) do { _Pragma("unroll") for (int n = 0; n < 2; ++n) _Pragma("unroll") for (int k = 0; k < 2; ++k) dst[n][k] = *(const LAS bf16x8*)(lds + PG8_SB(b, h) + boff + n * 2048 + k * 1024); } while (0)
; #define PG8_MMA(ai, bj, At, Bt) do { __builtin_amdgcn_s_setprio(1); _Pragma("unroll") for (int m = 0; m < 4; ++m) _Pragma("unroll") for (int n = 0; n < 2; ++n) _Pragma("unroll") for (int k = 0; k < 2; ++k) \
;         acc[ai][bj][m][n] = __builtin_amdgcn_mfma_f32_16x16x32_bf16(Bt[n][k], At[m][k], acc[ai][bj][m][n], 0, 0, 0); __builtin_amdgcn_s_setprio(0); } while (0)
; #define PG8_WAIT_V(n) asm volatile("s_waitcnt vmcnt(" #n ")" ::: "memory")
; #define PG8_WAIT_L(n) asm volatile("s_waitcnt lgkmcnt(" #n ")" ::: "memory")
; #define PG8_BAR __builtin_amdgcn_s_barrier()
; #define PG8_SCHED __builtin_amdgcn_sched_barrier(0)
; template <class Epi, class Sched>
; DI void gemm_phase(LAS unsigned char* lds, const int K, const Sched& S, const Epi& E, const int wid) {
;     ...
;             PG8_WAIT_V(8); PG8_WAIT_L(0); PG8_BAR; PG8_MMA(1, 0, At, B0); PG8_MMA(1, 1, At, B1); PG8_BAR; PG8_SCHED;
;             PG8_LDB(B0, 1, 0); PG8_LDB(B1, 1, 1); PG8_SCHED; PG8_LDA(At, 1, 0); PG8_STAGE(PG8_SA(0, 1), a2 + hstep, voffA);
;             PG8_WAIT_V(8); PG8_WAIT_L(0); PG8_BAR; PG8_MMA(0, 0, At, B0); PG8_MMA(0, 1, At, B1); PG8_BAR; PG8_SCHED;
	v_mfma_f32_16x16x32_bf16 v[60:63], v[128:131], v[160:163], v[60:63]
	v_mfma_f32_16x16x32_bf16 v[56:59], v[136:139], v[160:163], v[56:59]
	v_mfma_f32_16x16x32_bf16 v[52:55], v[128:131], v[168:171], v[52:55]
	v_mfma_f32_16x16x32_bf16 v[48:51], v[136:139], v[168:171], v[48:51]
	v_mfma_f32_16x16x32_bf16 v[36:39], v[128:131], v[176:179], v[36:39]
	v_mfma_f32_16x16x32_bf16 v[32:35], v[136:139], v[176:179], v[32:35]
	v_mfma_f32_16x16x32_bf16 v[20:23], v[128:131], v[192:195], v[20:23]
	v_mfma_f32_16x16x32_bf16 v[16:19], v[136:139], v[192:195], v[16:19]
	v_mfma_f32_16x16x32_bf16 v[60:63], v[132:135], v[164:167], v[60:63]
	v_mfma_f32_16x16x32_bf16 v[56:59], v[140:143], v[164:167], v[56:59]
	v_mfma_f32_16x16x32_bf16 v[52:55], v[132:135], v[172:175], v[52:55]
	v_mfma_f32_16x16x32_bf16 v[48:51], v[140:143], v[172:175], v[48:51]
	v_mfma_f32_16x16x32_bf16 v[36:39], v[132:135], v[180:183], v[36:39]
	v_mfma_f32_16x16x32_bf16 v[32:35], v[140:143], v[180:183], v[32:35]
	v_mfma_f32_16x16x32_bf16 v[20:23], v[132:135], v[196:199], v[20:23]
	v_mfma_f32_16x16x32_bf16 v[16:19], v[140:143], v[196:199], v[16:19]
	v_mfma_f32_16x16x32_bf16 v[44:47], v[144:147], v[160:163], v[44:47]
	v_mfma_f32_16x16x32_bf16 v[40:43], v[152:155], v[160:163], v[40:43]
	v_mfma_f32_16x16x32_bf16 v[28:31], v[144:147], v[168:171], v[28:31]
	v_mfma_f32_16x16x32_bf16 v[24:27], v[152:155], v[168:171], v[24:27]
	v_mfma_f32_16x16x32_bf16 v[12:15], v[144:147], v[176:179], v[12:15]
	v_mfma_f32_16x16x32_bf16 v[8:11], v[152:155], v[176:179], v[8:11]
	v_mfma_f32_16x16x32_bf16 v[4:7], v[144:147], v[192:195], v[4:7]
	v_mfma_f32_16x16x32_bf16 v[0:3], v[152:155], v[192:195], v[0:3]
	v_mfma_f32_16x16x32_bf16 v[44:47], v[148:151], v[164:167], v[44:47]
	v_mfma_f32_16x16x32_bf16 v[40:43], v[156:159], v[164:167], v[40:43]
	v_mfma_f32_16x16x32_bf16 v[28:31], v[148:151], v[172:175], v[28:31]
	v_mfma_f32_16x16x32_bf16 v[24:27], v[156:159], v[172:175], v[24:27]
	v_mfma_f32_16x16x32_bf16 v[12:15], v[148:151], v[180:183], v[12:15]
	v_mfma_f32_16x16x32_bf16 v[8:11], v[156:159], v[180:183], v[8:11]
	v_mfma_f32_16x16x32_bf16 v[4:7], v[148:151], v[196:199], v[4:7]
	v_mfma_f32_16x16x32_bf16 v[0:3], v[156:159], v[196:199], v[0:3]
	s_barrier
	v_add_u32_e32 v140, s96, v208
	v_add_u32_e32 v156, s90, v208
	ds_read_b128 v[128:131], v140
	ds_read_b128 v[132:135], v140 offset:1024
	ds_read_b128 v[136:139], v140 offset:2048
	ds_read_b128 v[140:143], v140 offset:3072
	ds_read_b128 v[144:147], v156
	ds_read_b128 v[148:151], v156 offset:1024
	ds_read_b128 v[152:155], v156 offset:2048
	ds_read_b128 v[156:159], v156 offset:3072
	s_add_u32 s6, s6, 0x80000
	s_addc_u32 s7, s7, 0
	s_mov_b32 m0, s29
	v_lshl_add_u64 v[214:215], s[6:7], 0, v[184:185]
	ds_read_b128 v[160:163], v210 offset:32768
	ds_read_b128 v[164:167], v210 offset:33792
	ds_read_b128 v[168:171], v210 offset:34816
	ds_read_b128 v[172:175], v210 offset:35840
	ds_read_b128 v[176:179], v210 offset:36864
	ds_read_b128 v[180:183], v210 offset:37888
	ds_read_b128 v[192:195], v210 offset:38912
	ds_read_b128 v[196:199], v210 offset:39936
	global_load_lds_dwordx4 v[214:215], off
	v_lshl_add_u64 v[214:215], s[6:7], 0, v[188:189]
	s_mov_b32 m0, s97
	s_nop 0
	global_load_lds_dwordx4 v[214:215], off
	s_waitcnt vmcnt(8)
	s_waitcnt lgkmcnt(0)
	s_barrier
	v_mfma_f32_16x16x32_bf16 v[124:127], v[128:131], v[160:163], v[124:127]
	v_mfma_f32_16x16x32_bf16 v[120:123], v[136:139], v[160:163], v[120:123]
	v_mfma_f32_16x16x32_bf16 v[116:119], v[128:131], v[168:171], v[116:119]
	v_mfma_f32_16x16x32_bf16 v[112:115], v[136:139], v[168:171], v[112:115]
	v_mfma_f32_16x16x32_bf16 v[100:103], v[128:131], v[176:179], v[100:103]
	v_mfma_f32_16x16x32_bf16 v[96:99], v[136:139], v[176:179], v[96:99]
	v_mfma_f32_16x16x32_bf16 v[84:87], v[128:131], v[192:195], v[84:87]
	v_mfma_f32_16x16x32_bf16 v[80:83], v[136:139], v[192:195], v[80:83]
	v_mfma_f32_16x16x32_bf16 v[124:127], v[132:135], v[164:167], v[124:127]
	v_mfma_f32_16x16x32_bf16 v[120:123], v[140:143], v[164:167], v[120:123]
	v_mfma_f32_16x16x32_bf16 v[116:119], v[132:135], v[172:175], v[116:119]
	v_mfma_f32_16x16x32_bf16 v[112:115], v[140:143], v[172:175], v[112:115]
	v_mfma_f32_16x16x32_bf16 v[100:103], v[132:135], v[180:183], v[100:103]
	v_mfma_f32_16x16x32_bf16 v[96:99], v[140:143], v[180:183], v[96:99]
	v_mfma_f32_16x16x32_bf16 v[84:87], v[132:135], v[196:199], v[84:87]
	v_mfma_f32_16x16x32_bf16 v[80:83], v[140:143], v[196:199], v[80:83]
	v_mfma_f32_16x16x32_bf16 v[108:111], v[144:147], v[160:163], v[108:111]
	v_mfma_f32_16x16x32_bf16 v[104:107], v[152:155], v[160:163], v[104:107]
	v_mfma_f32_16x16x32_bf16 v[92:95], v[144:147], v[168:171], v[92:95]
	v_mfma_f32_16x16x32_bf16 v[88:91], v[152:155], v[168:171], v[88:91]
	v_mfma_f32_16x16x32_bf16 v[76:79], v[144:147], v[176:179], v[76:79]
	v_mfma_f32_16x16x32_bf16 v[72:75], v[152:155], v[176:179], v[72:75]
	v_mfma_f32_16x16x32_bf16 v[68:71], v[144:147], v[192:195], v[68:71]
	v_mfma_f32_16x16x32_bf16 v[64:67], v[152:155], v[192:195], v[64:67]
	v_mfma_f32_16x16x32_bf16 v[108:111], v[148:151], v[164:167], v[108:111]
	v_mfma_f32_16x16x32_bf16 v[104:107], v[156:159], v[164:167], v[104:107]
	v_mfma_f32_16x16x32_bf16 v[92:95], v[148:151], v[172:175], v[92:95]
	v_mfma_f32_16x16x32_bf16 v[88:91], v[156:159], v[172:175], v[88:91]
	v_mfma_f32_16x16x32_bf16 v[76:79], v[148:151], v[180:183], v[76:79]
	v_mfma_f32_16x16x32_bf16 v[72:75], v[156:159], v[180:183], v[72:75]
	v_mfma_f32_16x16x32_bf16 v[68:71], v[148:151], v[196:199], v[68:71]
	v_mfma_f32_16x16x32_bf16 v[64:67], v[156:159], v[196:199], v[64:67]
	s_barrier
; #define PG8_STAGE(bufoff, gbase, voff) do { _Pragma("unroll") for (int _i = 0; _i < 2; ++_i) \
;         __builtin_amdgcn_global_load_lds((const unsigned*)((const char*)(gbase) + (voff)[_i]), (LAS unsigned*)(lds + (bufoff) + ldsw + _i * 8192), 16, 0, 0); } while (0)
; #define PG8_LDA(dst, b, h) do { _Pragma("unroll") for (int m = 0; m < 4; ++m) _Pragma("unroll") for (int k = 0; k < 2; ++k) dst[m][k] = *(const LAS bf16x8*)(lds + PG8_SA(b, h) + aoff + m * 2048 + k * 1024); } while (0)
; #define PG8_MMA(ai, bj, At, Bt) do { __builtin_amdgcn_s_setprio(1); _Pragma("unroll") for (int m = 0; m < 4; ++m) _Pragma("unroll") for (int n = 0; n < 2; ++n) _Pragma("unroll") for (int k = 0; k < 2; ++k) \
;         acc[ai][bj][m][n] = __builtin_amdgcn_mfma_f32_16x16x32_bf16(Bt[n][k], At[m][k], acc[ai][bj][m][n], 0, 0, 0); __builtin_amdgcn_s_setprio(0); } while (0)
; #define PG8_WAIT_V(n) asm volatile("s_waitcnt vmcnt(" #n ")" ::: "memory")
; #define PG8_WAIT_L(n) asm volatile("s_waitcnt lgkmcnt(" #n ")" ::: "memory")
; #define PG8_BAR __builtin_amdgcn_s_barrier()
; #define PG8_SCHED __builtin_amdgcn_sched_barrier(0)
; template <class Epi, class Sched>
; DI void gemm_phase(LAS unsigned char* lds, const int K, const Sched& S, const Epi& E, const int wid) {
;     ...
;             PG8_LDA(At, 1, 1); PG8_STAGE(PG8_SB(1, 0), b3, voffB); PG8_STAGE(PG8_SB(1, 1), b3 + hstep, voffB); PG8_STAGE(PG8_SA(1, 0), a3, voffA);
;             PG8_WAIT_V(8); PG8_WAIT_L(0); PG8_BAR; PG8_MMA(1, 0, At, B0); PG8_MMA(1, 1, At, B1); PG8_BAR; PG8_SCHED;
;         }
	s_mov_b32 m0, s94
	v_lshl_add_u64 v[200:201], v[200:201], 0, s[46:47]
	s_add_u32 s4, s4, 0x80080
	ds_read_b128 v[160:163], v210 offset:49152
	ds_read_b128 v[164:167], v210 offset:50176
	ds_read_b128 v[168:171], v210 offset:51200
	ds_read_b128 v[172:175], v210 offset:52224
	ds_read_b128 v[176:179], v210 offset:53248
	ds_read_b128 v[180:183], v210 offset:54272
	ds_read_b128 v[192:195], v210 offset:55296
	ds_read_b128 v[196:199], v210 offset:56320
	global_load_lds_dwordx4 v[200:201], off
	v_lshl_add_u64 v[200:201], v[202:203], 0, s[46:47]
	s_mov_b32 m0, s84
	s_addc_u32 s5, s5, 0
	global_load_lds_dwordx4 v[200:201], off
	v_lshl_add_u64 v[200:201], s[4:5], 0, v[186:187]
	s_mov_b32 m0, s86
	s_nop 0
	global_load_lds_dwordx4 v[200:201], off
	v_lshl_add_u64 v[200:201], s[4:5], 0, v[190:191]
	s_mov_b32 m0, s28
	s_nop 0
	global_load_lds_dwordx4 v[200:201], off
	v_lshl_add_u64 v[200:201], v[204:205], 0, s[46:47]
	s_mov_b32 m0, s91
	s_nop 0
	global_load_lds_dwordx4 v[200:201], off
	v_lshl_add_u64 v[200:201], v[212:213], 0, s[46:47]
	s_mov_b32 m0, s88
	s_nop 0
	global_load_lds_dwordx4 v[200:201], off
	s_waitcnt vmcnt(8)
	s_waitcnt lgkmcnt(0)
	s_barrier
	v_mfma_f32_16x16x32_bf16 v[60:63], v[128:131], v[160:163], v[60:63]
	v_mfma_f32_16x16x32_bf16 v[56:59], v[136:139], v[160:163], v[56:59]
	v_mfma_f32_16x16x32_bf16 v[52:55], v[128:131], v[168:171], v[52:55]
	v_mfma_f32_16x16x32_bf16 v[48:51], v[136:139], v[168:171], v[48:51]
	v_mfma_f32_16x16x32_bf16 v[36:39], v[128:131], v[176:179], v[36:39]
	v_mfma_f32_16x16x32_bf16 v[32:35], v[136:139], v[176:179], v[32:35]
	v_mfma_f32_16x16x32_bf16 v[20:23], v[128:131], v[192:195], v[20:23]
	v_mfma_f32_16x16x32_bf16 v[16:19], v[136:139], v[192:195], v[16:19]
	v_mfma_f32_16x16x32_bf16 v[60:63], v[132:135], v[164:167], v[60:63]
	v_mfma_f32_16x16x32_bf16 v[56:59], v[140:143], v[164:167], v[56:59]
	v_mfma_f32_16x16x32_bf16 v[52:55], v[132:135], v[172:175], v[52:55]
	v_mfma_f32_16x16x32_bf16 v[48:51], v[140:143], v[172:175], v[48:51]
	v_mfma_f32_16x16x32_bf16 v[36:39], v[132:135], v[180:183], v[36:39]
	v_mfma_f32_16x16x32_bf16 v[32:35], v[140:143], v[180:183], v[32:35]
	v_mfma_f32_16x16x32_bf16 v[20:23], v[132:135], v[196:199], v[20:23]
	v_mfma_f32_16x16x32_bf16 v[16:19], v[140:143], v[196:199], v[16:19]
	v_mfma_f32_16x16x32_bf16 v[44:47], v[144:147], v[160:163], v[44:47]
	v_mfma_f32_16x16x32_bf16 v[40:43], v[152:155], v[160:163], v[40:43]
	v_mfma_f32_16x16x32_bf16 v[28:31], v[144:147], v[168:171], v[28:31]
	v_mfma_f32_16x16x32_bf16 v[24:27], v[152:155], v[168:171], v[24:27]
	v_mfma_f32_16x16x32_bf16 v[12:15], v[144:147], v[176:179], v[12:15]
	v_mfma_f32_16x16x32_bf16 v[8:11], v[152:155], v[176:179], v[8:11]
	v_mfma_f32_16x16x32_bf16 v[4:7], v[144:147], v[192:195], v[4:7]
	v_mfma_f32_16x16x32_bf16 v[0:3], v[152:155], v[192:195], v[0:3]
	v_mfma_f32_16x16x32_bf16 v[44:47], v[148:151], v[164:167], v[44:47]
	v_mfma_f32_16x16x32_bf16 v[40:43], v[156:159], v[164:167], v[40:43]
	v_mfma_f32_16x16x32_bf16 v[28:31], v[148:151], v[172:175], v[28:31]
	v_mfma_f32_16x16x32_bf16 v[24:27], v[156:159], v[172:175], v[24:27]
	v_mfma_f32_16x16x32_bf16 v[12:15], v[148:151], v[180:183], v[12:15]
	v_mfma_f32_16x16x32_bf16 v[8:11], v[156:159], v[180:183], v[8:11]
	v_mfma_f32_16x16x32_bf16 v[4:7], v[148:151], v[196:199], v[4:7]
	v_mfma_f32_16x16x32_bf16 v[0:3], v[156:159], v[196:199], v[0:3]
	s_barrier
	s_cmp_ge_u32 s44, s11
	s_mov_b32 s6, s44
	s_cbranch_scc1 .LBB0_710

; #define PG8_STAGE(bufoff, gbase, voff) do { _Pragma("unroll") for (int _i = 0; _i < 2; ++_i) \
;         __builtin_amdgcn_global_load_lds((const unsigned*)((const char*)(gbase) + (voff)[_i]), (LAS unsigned*)(lds + (bufoff) + ldsw + _i * 8192), 16, 0, 0); } while (0)
; #define PG8_LDA(dst, b, h) do { _Pragma("unroll") for (int m = 0; m < 4; ++m) _Pragma("unroll") for (int k = 0; k < 2; ++k) dst[m][k] = *(const LAS bf16x8*)(lds + PG8_SA(b, h) + aoff + m * 2048 + k * 1024); } while (0)
; #define PG8_LDB(dst, b, h) do { _Pragma("unroll") for (int n = 0; n < 2; ++n) _Pragma("unroll") for (int k = 0; k < 2; ++k) dst[n][k] = *(const LAS bf16x8*)(lds + PG8_SB(b, h) + boff + n * 2048 + k * 1024); } while (0)
; #define PG8_MMA(ai, bj, At, Bt) do { __builtin_amdgcn_s_setprio(1); _Pragma("unroll") for (int m = 0; m < 4; ++m) _Pragma("unroll") for (int n = 0; n < 2; ++n) _Pragma("unroll") for (int k = 0; k < 2; ++k) \
;         acc[ai][bj][m][n] = __builtin_amdgcn_mfma_f32_16x16x32_bf16(Bt[n][k], At[m][k], acc[ai][bj][m][n], 0, 0, 0); __builtin_amdgcn_s_setprio(0); } while (0)
; #define PG8_WAIT_V(n) asm volatile("s_waitcnt vmcnt(" #n ")" ::: "memory")
; #define PG8_WAIT_L(n) asm volatile("s_waitcnt lgkmcnt(" #n ")" ::: "memory")
; #define PG8_BAR __builtin_amdgcn_s_barrier()
; #define PG8_SCHED __builtin_amdgcn_sched_barrier(0)
; template <class Epi, class Sched>
; DI void gemm_phase(LAS unsigned char* lds, const int K, const Sched& S, const Epi& E, const int wid) {
;     ...
;             const bool last = (t == nt - 2);
;             const char* a1 = cA + (size_t)(t + 1) * kstep;
;             const char* a2 = last ? nA : cA + (size_t)(t + 2) * kstep; const char* b2 = last ? nB : cB + (size_t)(t + 2) * kstep;
;             const char* a3 = a2 + kstep; const char* b3 = b2 + kstep;
;             if (last && has_next) S.a_ready(nxt);
;             PG8_LDB(B0, 0, 0); PG8_LDB(B1, 0, 1); PG8_SCHED; PG8_LDA(At, 0, 0); PG8_STAGE(PG8_SA(1, 1), a1 + hstep, voffA);
;             PG8_WAIT_V(8); PG8_WAIT_L(0); PG8_BAR; PG8_MMA(0, 0, At, B0); PG8_MMA(0, 1, At, B1); PG8_BAR; PG8_SCHED;
;             PG8_LDA(At, 0, 1); PG8_STAGE(PG8_SB(0, 0), b2, voffB); PG8_STAGE(PG8_SB(0, 1), b2 + hstep, voffB); PG8_STAGE(PG8_SA(0, 0), a2, voffA);
;             PG8_WAIT_V(8); PG8_WAIT_L(0); PG8_BAR; PG8_MMA(1, 0, At, B0); PG8_MMA(1, 1, At, B1); PG8_BAR; PG8_SCHED;
.LBB0_814:
	s_or_b32 s8, s54, 1
	s_lshl_b64 s[6:7], s[8:9], 7
	s_add_u32 s55, s50, s6
	s_addc_u32 s58, s51, s7
	s_add_i32 s8, s54, 2
	v_add_u32_e32 v108, s70, v198
	v_add_u32_e32 v124, s73, v198
	s_lshl_b64 s[56:57], s[8:9], 7
	ds_read_b128 v[96:99], v108
	ds_read_b128 v[100:103], v108 offset:1024
	ds_read_b128 v[104:107], v108 offset:2048
	ds_read_b128 v[108:111], v108 offset:3072
	ds_read_b128 v[112:115], v124
	ds_read_b128 v[116:119], v124 offset:1024
	ds_read_b128 v[120:123], v124 offset:2048
	ds_read_b128 v[124:127], v124 offset:3072
	s_add_u32 s59, s50, s56
	s_addc_u32 s60, s51, s57
	s_and_b64 s[6:7], s[4:5], exec
	s_cselect_b32 s7, s60, s35
	s_cselect_b32 s6, s59, s45
	s_add_u32 s56, s48, s56
	s_addc_u32 s57, s49, s57
	s_and_b64 s[4:5], s[4:5], exec
	s_cselect_b32 s5, s57, s31
	s_cselect_b32 s4, s56, s47
	s_add_u32 s56, s55, 0x80000
	s_addc_u32 s57, s58, 0
	s_mov_b32 m0, s89
	v_lshl_add_u64 v[194:195], s[56:57], 0, v[160:161]
	ds_read_b128 v[174:177], v199
	ds_read_b128 v[178:181], v199 offset:1024
	ds_read_b128 v[182:185], v199 offset:2048
	ds_read_b128 v[186:189], v199 offset:3072
	ds_read_b128 v[190:193], v199 offset:4096
	ds_read_b128 v[202:205], v199 offset:5120
	ds_read_b128 v[208:211], v199 offset:6144
	ds_read_b128 v[212:215], v199 offset:7168
	global_load_lds_dwordx4 v[194:195], off
	v_lshl_add_u64 v[194:195], s[56:57], 0, v[164:165]
	s_mov_b32 m0, s26
	s_nop 0
	global_load_lds_dwordx4 v[194:195], off
	s_waitcnt vmcnt(8)
	s_waitcnt lgkmcnt(0)
	s_barrier
	v_mfma_f32_16x16x32_bf16 v[156:159], v[96:99], v[174:177], v[156:159]
	v_mfma_f32_16x16x32_bf16 v[60:63], v[104:107], v[174:177], v[60:63]
	v_mfma_f32_16x16x32_bf16 v[148:151], v[96:99], v[182:185], v[148:151]
	v_mfma_f32_16x16x32_bf16 v[52:55], v[104:107], v[182:185], v[52:55]
	v_mfma_f32_16x16x32_bf16 v[144:147], v[96:99], v[190:193], v[144:147]
	v_mfma_f32_16x16x32_bf16 v[48:51], v[104:107], v[190:193], v[48:51]
	v_mfma_f32_16x16x32_bf16 v[152:155], v[96:99], v[208:211], v[152:155]
	v_mfma_f32_16x16x32_bf16 v[56:59], v[104:107], v[208:211], v[56:59]
	v_mfma_f32_16x16x32_bf16 v[156:159], v[100:103], v[178:181], v[156:159]
	v_mfma_f32_16x16x32_bf16 v[60:63], v[108:111], v[178:181], v[60:63]
	v_mfma_f32_16x16x32_bf16 v[148:151], v[100:103], v[186:189], v[148:151]
	v_mfma_f32_16x16x32_bf16 v[52:55], v[108:111], v[186:189], v[52:55]
	v_mfma_f32_16x16x32_bf16 v[144:147], v[100:103], v[202:205], v[144:147]
	v_mfma_f32_16x16x32_bf16 v[48:51], v[108:111], v[202:205], v[48:51]
	v_mfma_f32_16x16x32_bf16 v[152:155], v[100:103], v[212:215], v[152:155]
	v_mfma_f32_16x16x32_bf16 v[56:59], v[108:111], v[212:215], v[56:59]
	v_mfma_f32_16x16x32_bf16 v[140:143], v[112:115], v[174:177], v[140:143]
	v_mfma_f32_16x16x32_bf16 v[44:47], v[120:123], v[174:177], v[44:47]
	v_mfma_f32_16x16x32_bf16 v[132:135], v[112:115], v[182:185], v[132:135]
	v_mfma_f32_16x16x32_bf16 v[36:39], v[120:123], v[182:185], v[36:39]
	v_mfma_f32_16x16x32_bf16 v[128:131], v[112:115], v[190:193], v[128:131]
	v_mfma_f32_16x16x32_bf16 v[32:35], v[120:123], v[190:193], v[32:35]
	v_mfma_f32_16x16x32_bf16 v[136:139], v[112:115], v[208:211], v[136:139]
	v_mfma_f32_16x16x32_bf16 v[40:43], v[120:123], v[208:211], v[40:43]
	v_mfma_f32_16x16x32_bf16 v[140:143], v[116:119], v[178:181], v[140:143]
	v_mfma_f32_16x16x32_bf16 v[44:47], v[124:127], v[178:181], v[44:47]
	v_mfma_f32_16x16x32_bf16 v[132:135], v[116:119], v[186:189], v[132:135]
	v_mfma_f32_16x16x32_bf16 v[36:39], v[124:127], v[186:189], v[36:39]
	v_mfma_f32_16x16x32_bf16 v[128:131], v[116:119], v[202:205], v[128:131]
	v_mfma_f32_16x16x32_bf16 v[32:35], v[124:127], v[202:205], v[32:35]
	v_mfma_f32_16x16x32_bf16 v[136:139], v[116:119], v[212:215], v[136:139]
	v_mfma_f32_16x16x32_bf16 v[40:43], v[124:127], v[212:215], v[40:43]
	s_barrier
	s_mov_b32 m0, s27
	v_lshl_add_u64 v[194:195], s[4:5], 0, v[162:163]
	s_add_u32 s56, s4, 0x80000
	ds_read_b128 v[174:177], v199 offset:16384
	ds_read_b128 v[178:181], v199 offset:17408
	ds_read_b128 v[182:185], v199 offset:18432
	ds_read_b128 v[186:189], v199 offset:19456
	ds_read_b128 v[190:193], v199 offset:20480
	ds_read_b128 v[202:205], v199 offset:21504
	ds_read_b128 v[208:211], v199 offset:22528
	ds_read_b128 v[212:215], v199 offset:23552
	global_load_lds_dwordx4 v[194:195], off
	v_lshl_add_u64 v[216:217], s[4:5], 0, v[166:167]
	s_mov_b32 m0, s22
	s_addc_u32 s57, s5, 0
	global_load_lds_dwordx4 v[216:217], off
	v_lshl_add_u64 v[218:219], s[56:57], 0, v[162:163]
	s_mov_b32 m0, s23
	v_lshl_add_u64 v[220:221], s[6:7], 0, v[164:165]
	global_load_lds_dwordx4 v[218:219], off
	v_lshl_add_u64 v[218:219], s[56:57], 0, v[166:167]
	s_mov_b32 m0, s87
	s_nop 0
	global_load_lds_dwordx4 v[218:219], off
	v_lshl_add_u64 v[218:219], s[6:7], 0, v[160:161]
	s_mov_b32 m0, s85
	s_nop 0
	global_load_lds_dwordx4 v[218:219], off
	s_mov_b32 m0, s33
	s_nop 0
	global_load_lds_dwordx4 v[220:221], off
	s_waitcnt vmcnt(8)
	s_waitcnt lgkmcnt(0)
	s_barrier
; #define PG8_STAGE(bufoff, gbase, voff) do { _Pragma("unroll") for (int _i = 0; _i < 2; ++_i) \
;         __builtin_amdgcn_global_load_lds((const unsigned*)((const char*)(gbase) + (voff)[_i]), (LAS unsigned*)(lds + (bufoff) + ldsw + _i * 8192), 16, 0, 0); } while (0)
; #define PG8_LDA(dst, b, h) do { _Pragma("unroll") for (int m = 0; m < 4; ++m) _Pragma("unroll") for (int k = 0; k < 2; ++k) dst[m][k] = *(const LAS bf16x8*)(lds + PG8_SA(b, h) + aoff + m * 2048 + k * 1024); } while (0)
; #define PG8_LDB(dst, b, h) do { _Pragma("unroll") for (int n = 0; n < 2; ++n) _Pragma("unroll") for (int k = 0; k < 2; ++k) dst[n][k] = *(const LAS bf16x8*)(lds + PG8_SB(b, h) + boff + n * 2048 + k * 1024); } while (0)
; #define PG8_MMA(ai, bj, At, Bt) do { __builtin_amdgcn_s_setprio(1); _Pragma("unroll") for (int m = 0; m < 4; ++m) _Pragma("unroll") for (int n = 0; n < 2; ++n) _Pragma("unroll") for (int k = 0; k < 2; ++k) \
;         acc[ai][bj][m][n] = __builtin_amdgcn_mfma_f32_16x16x32_bf16(Bt[n][k], At[m][k], acc[ai][bj][m][n], 0, 0, 0); __builtin_amdgcn_s_setprio(0); } while (0)
; #define PG8_WAIT_V(n) asm volatile("s_waitcnt vmcnt(" #n ")" ::: "memory")
; #define PG8_WAIT_L(n) asm volatile("s_waitcnt lgkmcnt(" #n ")" ::: "memory")
; #define PG8_BAR __builtin_amdgcn_s_barrier()
; #define PG8_SCHED __builtin_amdgcn_sched_barrier(0)
; template <class Epi, class Sched>
; DI void gemm_phase(LAS unsigned char* lds, const int K, const Sched& S, const Epi& E, const int wid) {
;     ...
;             PG8_WAIT_V(8); PG8_WAIT_L(0); PG8_BAR; PG8_MMA(1, 0, At, B0); PG8_MMA(1, 1, At, B1); PG8_BAR; PG8_SCHED;
;             PG8_LDB(B0, 1, 0); PG8_LDB(B1, 1, 1); PG8_SCHED; PG8_LDA(At, 1, 0); PG8_STAGE(PG8_SA(0, 1), a2 + hstep, voffA);
;             PG8_WAIT_V(8); PG8_WAIT_L(0); PG8_BAR; PG8_MMA(0, 0, At, B0); PG8_MMA(0, 1, At, B1); PG8_BAR; PG8_SCHED;
	v_mfma_f32_16x16x32_bf16 v[92:95], v[96:99], v[174:177], v[92:95]
	v_mfma_f32_16x16x32_bf16 v[28:31], v[104:107], v[174:177], v[28:31]
	v_mfma_f32_16x16x32_bf16 v[84:87], v[96:99], v[182:185], v[84:87]
	v_mfma_f32_16x16x32_bf16 v[20:23], v[104:107], v[182:185], v[20:23]
	v_mfma_f32_16x16x32_bf16 v[80:83], v[96:99], v[190:193], v[80:83]
	v_mfma_f32_16x16x32_bf16 v[16:19], v[104:107], v[190:193], v[16:19]
	v_mfma_f32_16x16x32_bf16 v[88:91], v[96:99], v[208:211], v[88:91]
	v_mfma_f32_16x16x32_bf16 v[24:27], v[104:107], v[208:211], v[24:27]
	v_mfma_f32_16x16x32_bf16 v[92:95], v[100:103], v[178:181], v[92:95]
	v_mfma_f32_16x16x32_bf16 v[28:31], v[108:111], v[178:181], v[28:31]
	v_mfma_f32_16x16x32_bf16 v[84:87], v[100:103], v[186:189], v[84:87]
	v_mfma_f32_16x16x32_bf16 v[20:23], v[108:111], v[186:189], v[20:23]
	v_mfma_f32_16x16x32_bf16 v[80:83], v[100:103], v[202:205], v[80:83]
	v_mfma_f32_16x16x32_bf16 v[16:19], v[108:111], v[202:205], v[16:19]
	v_mfma_f32_16x16x32_bf16 v[88:91], v[100:103], v[212:215], v[88:91]
	v_mfma_f32_16x16x32_bf16 v[24:27], v[108:111], v[212:215], v[24:27]
	v_mfma_f32_16x16x32_bf16 v[76:79], v[112:115], v[174:177], v[76:79]
	v_mfma_f32_16x16x32_bf16 v[12:15], v[120:123], v[174:177], v[12:15]
	v_mfma_f32_16x16x32_bf16 v[68:71], v[112:115], v[182:185], v[68:71]
	v_mfma_f32_16x16x32_bf16 v[4:7], v[120:123], v[182:185], v[4:7]
	v_mfma_f32_16x16x32_bf16 v[64:67], v[112:115], v[190:193], v[64:67]
	v_mfma_f32_16x16x32_bf16 v[0:3], v[120:123], v[190:193], v[0:3]
	v_mfma_f32_16x16x32_bf16 v[72:75], v[112:115], v[208:211], v[72:75]
	v_mfma_f32_16x16x32_bf16 v[8:11], v[120:123], v[208:211], v[8:11]
	v_mfma_f32_16x16x32_bf16 v[76:79], v[116:119], v[178:181], v[76:79]
	v_mfma_f32_16x16x32_bf16 v[12:15], v[124:127], v[178:181], v[12:15]
	v_mfma_f32_16x16x32_bf16 v[68:71], v[116:119], v[186:189], v[68:71]
	v_mfma_f32_16x16x32_bf16 v[4:7], v[124:127], v[186:189], v[4:7]
	v_mfma_f32_16x16x32_bf16 v[64:67], v[116:119], v[202:205], v[64:67]
	v_mfma_f32_16x16x32_bf16 v[0:3], v[124:127], v[202:205], v[0:3]
	v_mfma_f32_16x16x32_bf16 v[72:75], v[116:119], v[212:215], v[72:75]
	v_mfma_f32_16x16x32_bf16 v[8:11], v[124:127], v[212:215], v[8:11]
	s_barrier
	v_add_u32_e32 v108, s96, v198
	v_add_u32_e32 v124, s90, v198
	ds_read_b128 v[96:99], v108
	ds_read_b128 v[100:103], v108 offset:1024
	ds_read_b128 v[104:107], v108 offset:2048
	ds_read_b128 v[108:111], v108 offset:3072
	ds_read_b128 v[112:115], v124
	ds_read_b128 v[116:119], v124 offset:1024
	ds_read_b128 v[120:123], v124 offset:2048
	ds_read_b128 v[124:127], v124 offset:3072
	s_add_u32 s6, s6, 0x80000
	s_addc_u32 s7, s7, 0
	s_mov_b32 m0, s29
	v_lshl_add_u64 v[222:223], s[6:7], 0, v[160:161]
	ds_read_b128 v[174:177], v199 offset:32768
	ds_read_b128 v[178:181], v199 offset:33792
	ds_read_b128 v[182:185], v199 offset:34816
	ds_read_b128 v[186:189], v199 offset:35840
	ds_read_b128 v[190:193], v199 offset:36864
	ds_read_b128 v[202:205], v199 offset:37888
	ds_read_b128 v[208:211], v199 offset:38912
	ds_read_b128 v[212:215], v199 offset:39936
	global_load_lds_dwordx4 v[222:223], off
	v_lshl_add_u64 v[222:223], s[6:7], 0, v[164:165]
	s_mov_b32 m0, s97
	s_nop 0
	global_load_lds_dwordx4 v[222:223], off
	s_waitcnt vmcnt(8)
	s_waitcnt lgkmcnt(0)
	s_barrier
	v_mfma_f32_16x16x32_bf16 v[156:159], v[96:99], v[174:177], v[156:159]
	v_mfma_f32_16x16x32_bf16 v[60:63], v[104:107], v[174:177], v[60:63]
	v_mfma_f32_16x16x32_bf16 v[148:151], v[96:99], v[182:185], v[148:151]
	v_mfma_f32_16x16x32_bf16 v[52:55], v[104:107], v[182:185], v[52:55]
	v_mfma_f32_16x16x32_bf16 v[144:147], v[96:99], v[190:193], v[144:147]
	v_mfma_f32_16x16x32_bf16 v[48:51], v[104:107], v[190:193], v[48:51]
	v_mfma_f32_16x16x32_bf16 v[152:155], v[96:99], v[208:211], v[152:155]
	v_mfma_f32_16x16x32_bf16 v[56:59], v[104:107], v[208:211], v[56:59]
	v_mfma_f32_16x16x32_bf16 v[156:159], v[100:103], v[178:181], v[156:159]
	v_mfma_f32_16x16x32_bf16 v[60:63], v[108:111], v[178:181], v[60:63]
	v_mfma_f32_16x16x32_bf16 v[148:151], v[100:103], v[186:189], v[148:151]
	v_mfma_f32_16x16x32_bf16 v[52:55], v[108:111], v[186:189], v[52:55]
	v_mfma_f32_16x16x32_bf16 v[144:147], v[100:103], v[202:205], v[144:147]
	v_mfma_f32_16x16x32_bf16 v[48:51], v[108:111], v[202:205], v[48:51]
	v_mfma_f32_16x16x32_bf16 v[152:155], v[100:103], v[212:215], v[152:155]
	v_mfma_f32_16x16x32_bf16 v[56:59], v[108:111], v[212:215], v[56:59]
	v_mfma_f32_16x16x32_bf16 v[140:143], v[112:115], v[174:177], v[140:143]
	v_mfma_f32_16x16x32_bf16 v[44:47], v[120:123], v[174:177], v[44:47]
	v_mfma_f32_16x16x32_bf16 v[132:135], v[112:115], v[182:185], v[132:135]
	v_mfma_f32_16x16x32_bf16 v[36:39], v[120:123], v[182:185], v[36:39]
	v_mfma_f32_16x16x32_bf16 v[128:131], v[112:115], v[190:193], v[128:131]
	v_mfma_f32_16x16x32_bf16 v[32:35], v[120:123], v[190:193], v[32:35]
	v_mfma_f32_16x16x32_bf16 v[136:139], v[112:115], v[208:211], v[136:139]
	v_mfma_f32_16x16x32_bf16 v[40:43], v[120:123], v[208:211], v[40:43]
	v_mfma_f32_16x16x32_bf16 v[140:143], v[116:119], v[178:181], v[140:143]
	v_mfma_f32_16x16x32_bf16 v[44:47], v[124:127], v[178:181], v[44:47]
	v_mfma_f32_16x16x32_bf16 v[132:135], v[116:119], v[186:189], v[132:135]
	v_mfma_f32_16x16x32_bf16 v[36:39], v[124:127], v[186:189], v[36:39]
	v_mfma_f32_16x16x32_bf16 v[128:131], v[116:119], v[202:205], v[128:131]
	v_mfma_f32_16x16x32_bf16 v[32:35], v[124:127], v[202:205], v[32:35]
	v_mfma_f32_16x16x32_bf16 v[136:139], v[116:119], v[212:215], v[136:139]
	v_mfma_f32_16x16x32_bf16 v[40:43], v[124:127], v[212:215], v[40:43]
	s_barrier
; #define PG8_STAGE(bufoff, gbase, voff) do { _Pragma("unroll") for (int _i = 0; _i < 2; ++_i) \
;         __builtin_amdgcn_global_load_lds((const unsigned*)((const char*)(gbase) + (voff)[_i]), (LAS unsigned*)(lds + (bufoff) + ldsw + _i * 8192), 16, 0, 0); } while (0)
; #define PG8_LDA(dst, b, h) do { _Pragma("unroll") for (int m = 0; m < 4; ++m) _Pragma("unroll") for (int k = 0; k < 2; ++k) dst[m][k] = *(const LAS bf16x8*)(lds + PG8_SA(b, h) + aoff + m * 2048 + k * 1024); } while (0)
; #define PG8_MMA(ai, bj, At, Bt) do { __builtin_amdgcn_s_setprio(1); _Pragma("unroll") for (int m = 0; m < 4; ++m) _Pragma("unroll") for (int n = 0; n < 2; ++n) _Pragma("unroll") for (int k = 0; k < 2; ++k) \
;         acc[ai][bj][m][n] = __builtin_amdgcn_mfma_f32_16x16x32_bf16(Bt[n][k], At[m][k], acc[ai][bj][m][n], 0, 0, 0); __builtin_amdgcn_s_setprio(0); } while (0)
; #define PG8_WAIT_V(n) asm volatile("s_waitcnt vmcnt(" #n ")" ::: "memory")
; #define PG8_WAIT_L(n) asm volatile("s_waitcnt lgkmcnt(" #n ")" ::: "memory")
; #define PG8_BAR __builtin_amdgcn_s_barrier()
; #define PG8_SCHED __builtin_amdgcn_sched_barrier(0)
; template <class Epi, class Sched>
; DI void gemm_phase(LAS unsigned char* lds, const int K, const Sched& S, const Epi& E, const int wid) {
;     ...
;             PG8_LDA(At, 1, 1); PG8_STAGE(PG8_SB(1, 0), b3, voffB); PG8_STAGE(PG8_SB(1, 1), b3 + hstep, voffB); PG8_STAGE(PG8_SA(1, 0), a3, voffA);
;             PG8_WAIT_V(8); PG8_WAIT_L(0); PG8_BAR; PG8_MMA(1, 0, At, B0); PG8_MMA(1, 1, At, B1); PG8_BAR; PG8_SCHED;
;         }
	s_mov_b32 m0, s94
	v_lshl_add_u64 v[194:195], v[194:195], 0, s[18:19]
	s_add_u32 s4, s4, 0x80080
	ds_read_b128 v[174:177], v199 offset:49152
	ds_read_b128 v[178:181], v199 offset:50176
	ds_read_b128 v[182:185], v199 offset:51200
	ds_read_b128 v[186:189], v199 offset:52224
	ds_read_b128 v[190:193], v199 offset:53248
	ds_read_b128 v[202:205], v199 offset:54272
	ds_read_b128 v[208:211], v199 offset:55296
	ds_read_b128 v[212:215], v199 offset:56320
	global_load_lds_dwordx4 v[194:195], off
	v_lshl_add_u64 v[194:195], v[216:217], 0, s[18:19]
	s_mov_b32 m0, s84
	s_addc_u32 s5, s5, 0
	global_load_lds_dwordx4 v[194:195], off
	v_lshl_add_u64 v[194:195], s[4:5], 0, v[162:163]
	s_mov_b32 m0, s86
	s_nop 0
	global_load_lds_dwordx4 v[194:195], off
	v_lshl_add_u64 v[194:195], s[4:5], 0, v[166:167]
	s_mov_b32 m0, s28
	s_nop 0
	global_load_lds_dwordx4 v[194:195], off
	v_lshl_add_u64 v[194:195], v[218:219], 0, s[18:19]
	s_mov_b32 m0, s91
	s_nop 0
	global_load_lds_dwordx4 v[194:195], off
	v_lshl_add_u64 v[194:195], v[220:221], 0, s[18:19]
	s_mov_b32 m0, s88
	s_nop 0
	global_load_lds_dwordx4 v[194:195], off
	s_waitcnt vmcnt(8)
	s_waitcnt lgkmcnt(0)
	s_barrier
	v_mfma_f32_16x16x32_bf16 v[92:95], v[96:99], v[174:177], v[92:95]
	v_mfma_f32_16x16x32_bf16 v[28:31], v[104:107], v[174:177], v[28:31]
	v_mfma_f32_16x16x32_bf16 v[84:87], v[96:99], v[182:185], v[84:87]
	v_mfma_f32_16x16x32_bf16 v[20:23], v[104:107], v[182:185], v[20:23]
	v_mfma_f32_16x16x32_bf16 v[80:83], v[96:99], v[190:193], v[80:83]
	v_mfma_f32_16x16x32_bf16 v[16:19], v[104:107], v[190:193], v[16:19]
	v_mfma_f32_16x16x32_bf16 v[88:91], v[96:99], v[208:211], v[88:91]
	v_mfma_f32_16x16x32_bf16 v[24:27], v[104:107], v[208:211], v[24:27]
	v_mfma_f32_16x16x32_bf16 v[92:95], v[100:103], v[178:181], v[92:95]
	v_mfma_f32_16x16x32_bf16 v[28:31], v[108:111], v[178:181], v[28:31]
	v_mfma_f32_16x16x32_bf16 v[84:87], v[100:103], v[186:189], v[84:87]
	v_mfma_f32_16x16x32_bf16 v[20:23], v[108:111], v[186:189], v[20:23]
	v_mfma_f32_16x16x32_bf16 v[80:83], v[100:103], v[202:205], v[80:83]
	v_mfma_f32_16x16x32_bf16 v[16:19], v[108:111], v[202:205], v[16:19]
	v_mfma_f32_16x16x32_bf16 v[88:91], v[100:103], v[212:215], v[88:91]
	v_mfma_f32_16x16x32_bf16 v[24:27], v[108:111], v[212:215], v[24:27]
	v_mfma_f32_16x16x32_bf16 v[76:79], v[112:115], v[174:177], v[76:79]
	v_mfma_f32_16x16x32_bf16 v[12:15], v[120:123], v[174:177], v[12:15]
	v_mfma_f32_16x16x32_bf16 v[68:71], v[112:115], v[182:185], v[68:71]
	v_mfma_f32_16x16x32_bf16 v[4:7], v[120:123], v[182:185], v[4:7]
	v_mfma_f32_16x16x32_bf16 v[64:67], v[112:115], v[190:193], v[64:67]
	v_mfma_f32_16x16x32_bf16 v[0:3], v[120:123], v[190:193], v[0:3]
	v_mfma_f32_16x16x32_bf16 v[72:75], v[112:115], v[208:211], v[72:75]
	v_mfma_f32_16x16x32_bf16 v[8:11], v[120:123], v[208:211], v[8:11]
	v_mfma_f32_16x16x32_bf16 v[76:79], v[116:119], v[178:181], v[76:79]
	v_mfma_f32_16x16x32_bf16 v[12:15], v[124:127], v[178:181], v[12:15]
	v_mfma_f32_16x16x32_bf16 v[68:71], v[116:119], v[186:189], v[68:71]
	v_mfma_f32_16x16x32_bf16 v[4:7], v[124:127], v[186:189], v[4:7]
	v_mfma_f32_16x16x32_bf16 v[64:67], v[116:119], v[202:205], v[64:67]
	v_mfma_f32_16x16x32_bf16 v[0:3], v[124:127], v[202:205], v[0:3]
	v_mfma_f32_16x16x32_bf16 v[72:75], v[116:119], v[212:215], v[72:75]
	v_mfma_f32_16x16x32_bf16 v[8:11], v[124:127], v[212:215], v[8:11]
	s_barrier
	s_cmp_gt_u32 s54, 29
	s_mov_b32 s54, s8
	s_cbranch_scc1 .LBB0_818

; #define PG8_STAGE(bufoff, gbase, voff) do { _Pragma("unroll") for (int _i = 0; _i < 2; ++_i) \
;         __builtin_amdgcn_global_load_lds((const unsigned*)((const char*)(gbase) + (voff)[_i]), (LAS unsigned*)(lds + (bufoff) + ldsw + _i * 8192), 16, 0, 0); } while (0)
; #define PG8_LDA(dst, b, h) do { _Pragma("unroll") for (int m = 0; m < 4; ++m) _Pragma("unroll") for (int k = 0; k < 2; ++k) dst[m][k] = *(const LAS bf16x8*)(lds + PG8_SA(b, h) + aoff + m * 2048 + k * 1024); } while (0)
; #define PG8_LDB(dst, b, h) do { _Pragma("unroll") for (int n = 0; n < 2; ++n) _Pragma("unroll") for (int k = 0; k < 2; ++k) dst[n][k] = *(const LAS bf16x8*)(lds + PG8_SB(b, h) + boff + n * 2048 + k * 1024); } while (0)
; #define PG8_MMA(ai, bj, At, Bt) do { __builtin_amdgcn_s_setprio(1); _Pragma("unroll") for (int m = 0; m < 4; ++m) _Pragma("unroll") for (int n = 0; n < 2; ++n) _Pragma("unroll") for (int k = 0; k < 2; ++k) \
;         acc[ai][bj][m][n] = __builtin_amdgcn_mfma_f32_16x16x32_bf16(Bt[n][k], At[m][k], acc[ai][bj][m][n], 0, 0, 0); __builtin_amdgcn_s_setprio(0); } while (0)
; #define PG8_WAIT_V(n) asm volatile("s_waitcnt vmcnt(" #n ")" ::: "memory")
; #define PG8_WAIT_L(n) asm volatile("s_waitcnt lgkmcnt(" #n ")" ::: "memory")
; #define PG8_BAR __builtin_amdgcn_s_barrier()
; #define PG8_SCHED __builtin_amdgcn_sched_barrier(0)
; template <class Epi, class Sched>
; DI void gemm_phase(LAS unsigned char* lds, const int K, const Sched& S, const Epi& E, const int wid) {
;     ...
;             const bool last = (t == nt - 2);
;             const char* a1 = cA + (size_t)(t + 1) * kstep;
;             const char* a2 = last ? nA : cA + (size_t)(t + 2) * kstep; const char* b2 = last ? nB : cB + (size_t)(t + 2) * kstep;
;             const char* a3 = a2 + kstep; const char* b3 = b2 + kstep;
;             if (last && has_next) S.a_ready(nxt);
;             PG8_LDB(B0, 0, 0); PG8_LDB(B1, 0, 1); PG8_SCHED; PG8_LDA(At, 0, 0); PG8_STAGE(PG8_SA(1, 1), a1 + hstep, voffA);
;             PG8_WAIT_V(8); PG8_WAIT_L(0); PG8_BAR; PG8_MMA(0, 0, At, B0); PG8_MMA(0, 1, At, B1); PG8_BAR; PG8_SCHED;
;             PG8_LDA(At, 0, 1); PG8_STAGE(PG8_SB(0, 0), b2, voffB); PG8_STAGE(PG8_SB(0, 1), b2 + hstep, voffB); PG8_STAGE(PG8_SA(0, 0), a2, voffA);
;             PG8_WAIT_V(8); PG8_WAIT_L(0); PG8_BAR; PG8_MMA(1, 0, At, B0); PG8_MMA(1, 1, At, B1); PG8_BAR; PG8_SCHED;
.LBB0_1068:
	ds_read_b128 v[128:131], v179
	ds_read_b128 v[132:135], v179 offset:1024
	ds_read_b128 v[136:139], v179 offset:2048
	ds_read_b128 v[140:143], v179 offset:3072
	ds_read_b128 v[144:147], v180
	ds_read_b128 v[160:163], v180 offset:1024
	ds_read_b128 v[164:167], v180 offset:2048
	ds_read_b128 v[168:171], v180 offset:3072
	s_add_i32 s38, s6, 2
	s_add_u32 s4, s18, 0x100
	s_addc_u32 s5, s19, 0
	s_cmp_eq_u32 s35, s6
	s_cselect_b32 s6, s16, s36
	s_cselect_b32 s21, s15, s5
	s_cselect_b32 s20, s14, s4
	s_cselect_b32 s7, s17, s37
	s_mov_b32 m0, s89
	v_lshl_add_u64 v[212:213], s[18:19], 0, v[156:157]
	ds_read_b128 v[172:175], v181
	ds_read_b128 v[182:185], v181 offset:1024
	ds_read_b128 v[186:189], v181 offset:2048
	ds_read_b128 v[190:193], v181 offset:3072
	ds_read_b128 v[194:197], v181 offset:4096
	ds_read_b128 v[198:201], v181 offset:5120
	ds_read_b128 v[202:205], v181 offset:6144
	ds_read_b128 v[208:211], v181 offset:7168
	global_load_lds_dwordx4 v[212:213], off
	v_lshl_add_u64 v[212:213], s[18:19], 0, v[158:159]
	s_mov_b32 m0, s26
	s_nop 0
	global_load_lds_dwordx4 v[212:213], off
	s_waitcnt vmcnt(8)
	s_waitcnt lgkmcnt(0)
	s_barrier
	v_mfma_f32_16x16x32_bf16 v[124:127], v[128:131], v[172:175], v[124:127]
	v_mfma_f32_16x16x32_bf16 v[120:123], v[136:139], v[172:175], v[120:123]
	v_mfma_f32_16x16x32_bf16 v[116:119], v[128:131], v[186:189], v[116:119]
	v_mfma_f32_16x16x32_bf16 v[112:115], v[136:139], v[186:189], v[112:115]
	v_mfma_f32_16x16x32_bf16 v[100:103], v[128:131], v[194:197], v[100:103]
	v_mfma_f32_16x16x32_bf16 v[96:99], v[136:139], v[194:197], v[96:99]
	v_mfma_f32_16x16x32_bf16 v[84:87], v[128:131], v[202:205], v[84:87]
	v_mfma_f32_16x16x32_bf16 v[80:83], v[136:139], v[202:205], v[80:83]
	v_mfma_f32_16x16x32_bf16 v[124:127], v[132:135], v[182:185], v[124:127]
	v_mfma_f32_16x16x32_bf16 v[120:123], v[140:143], v[182:185], v[120:123]
	v_mfma_f32_16x16x32_bf16 v[116:119], v[132:135], v[190:193], v[116:119]
	v_mfma_f32_16x16x32_bf16 v[112:115], v[140:143], v[190:193], v[112:115]
	v_mfma_f32_16x16x32_bf16 v[100:103], v[132:135], v[198:201], v[100:103]
	v_mfma_f32_16x16x32_bf16 v[96:99], v[140:143], v[198:201], v[96:99]
	v_mfma_f32_16x16x32_bf16 v[84:87], v[132:135], v[208:211], v[84:87]
	v_mfma_f32_16x16x32_bf16 v[80:83], v[140:143], v[208:211], v[80:83]
	v_mfma_f32_16x16x32_bf16 v[108:111], v[144:147], v[172:175], v[108:111]
	v_mfma_f32_16x16x32_bf16 v[104:107], v[164:167], v[172:175], v[104:107]
	v_mfma_f32_16x16x32_bf16 v[92:95], v[144:147], v[186:189], v[92:95]
	v_mfma_f32_16x16x32_bf16 v[88:91], v[164:167], v[186:189], v[88:91]
	v_mfma_f32_16x16x32_bf16 v[76:79], v[144:147], v[194:197], v[76:79]
	v_mfma_f32_16x16x32_bf16 v[72:75], v[164:167], v[194:197], v[72:75]
	v_mfma_f32_16x16x32_bf16 v[68:71], v[144:147], v[202:205], v[68:71]
	v_mfma_f32_16x16x32_bf16 v[64:67], v[164:167], v[202:205], v[64:67]
	v_mfma_f32_16x16x32_bf16 v[108:111], v[160:163], v[182:185], v[108:111]
	v_mfma_f32_16x16x32_bf16 v[104:107], v[168:171], v[182:185], v[104:107]
	v_mfma_f32_16x16x32_bf16 v[92:95], v[160:163], v[190:193], v[92:95]
	v_mfma_f32_16x16x32_bf16 v[88:91], v[168:171], v[190:193], v[88:91]
	v_mfma_f32_16x16x32_bf16 v[76:79], v[160:163], v[198:201], v[76:79]
	v_mfma_f32_16x16x32_bf16 v[72:75], v[168:171], v[198:201], v[72:75]
	v_mfma_f32_16x16x32_bf16 v[68:71], v[160:163], v[208:211], v[68:71]
	v_mfma_f32_16x16x32_bf16 v[64:67], v[168:171], v[208:211], v[64:67]
	s_barrier
	s_mov_b32 m0, s27
	v_lshl_add_u64 v[212:213], s[6:7], 0, v[150:151]
	s_add_u32 s18, s6, 0x164000
	ds_read_b128 v[172:175], v181 offset:16384
	ds_read_b128 v[182:185], v181 offset:17408
	ds_read_b128 v[186:189], v181 offset:18432
	ds_read_b128 v[190:193], v181 offset:19456
	ds_read_b128 v[194:197], v181 offset:20480
	ds_read_b128 v[198:201], v181 offset:21504
	ds_read_b128 v[202:205], v181 offset:22528
	ds_read_b128 v[208:211], v181 offset:23552
	global_load_lds_dwordx4 v[212:213], off
	v_lshl_add_u64 v[214:215], s[6:7], 0, v[154:155]
	s_mov_b32 m0, s22
	s_addc_u32 s19, s7, 0
	global_load_lds_dwordx4 v[214:215], off
	v_lshl_add_u64 v[216:217], s[18:19], 0, v[150:151]
	s_mov_b32 m0, s23
	v_lshl_add_u64 v[218:219], s[20:21], 0, v[152:153]
	global_load_lds_dwordx4 v[216:217], off
	v_lshl_add_u64 v[216:217], s[18:19], 0, v[154:155]
	s_mov_b32 m0, s87
	s_nop 0
	global_load_lds_dwordx4 v[216:217], off
	v_lshl_add_u64 v[216:217], s[20:21], 0, v[148:149]
	s_mov_b32 m0, s85
	s_nop 0
	global_load_lds_dwordx4 v[216:217], off
	s_mov_b32 m0, s33
	s_nop 0
	global_load_lds_dwordx4 v[218:219], off
	s_waitcnt vmcnt(8)
	s_waitcnt lgkmcnt(0)
	s_barrier
; #define PG8_STAGE(bufoff, gbase, voff) do { _Pragma("unroll") for (int _i = 0; _i < 2; ++_i) \
;         __builtin_amdgcn_global_load_lds((const unsigned*)((const char*)(gbase) + (voff)[_i]), (LAS unsigned*)(lds + (bufoff) + ldsw + _i * 8192), 16, 0, 0); } while (0)
; #define PG8_LDA(dst, b, h) do { _Pragma("unroll") for (int m = 0; m < 4; ++m) _Pragma("unroll") for (int k = 0; k < 2; ++k) dst[m][k] = *(const LAS bf16x8*)(lds + PG8_SA(b, h) + aoff + m * 2048 + k * 1024); } while (0)
; #define PG8_LDB(dst, b, h) do { _Pragma("unroll") for (int n = 0; n < 2; ++n) _Pragma("unroll") for (int k = 0; k < 2; ++k) dst[n][k] = *(const LAS bf16x8*)(lds + PG8_SB(b, h) + boff + n * 2048 + k * 1024); } while (0)
; #define PG8_MMA(ai, bj, At, Bt) do { __builtin_amdgcn_s_setprio(1); _Pragma("unroll") for (int m = 0; m < 4; ++m) _Pragma("unroll") for (int n = 0; n < 2; ++n) _Pragma("unroll") for (int k = 0; k < 2; ++k) \
;         acc[ai][bj][m][n] = __builtin_amdgcn_mfma_f32_16x16x32_bf16(Bt[n][k], At[m][k], acc[ai][bj][m][n], 0, 0, 0); __builtin_amdgcn_s_setprio(0); } while (0)
; #define PG8_WAIT_V(n) asm volatile("s_waitcnt vmcnt(" #n ")" ::: "memory")
; #define PG8_WAIT_L(n) asm volatile("s_waitcnt lgkmcnt(" #n ")" ::: "memory")
; #define PG8_BAR __builtin_amdgcn_s_barrier()
; #define PG8_SCHED __builtin_amdgcn_sched_barrier(0)
; template <class Epi, class Sched>
; DI void gemm_phase(LAS unsigned char* lds, const int K, const Sched& S, const Epi& E, const int wid) {
;     ...
;             PG8_WAIT_V(8); PG8_WAIT_L(0); PG8_BAR; PG8_MMA(1, 0, At, B0); PG8_MMA(1, 1, At, B1); PG8_BAR; PG8_SCHED;
;             PG8_LDB(B0, 1, 0); PG8_LDB(B1, 1, 1); PG8_SCHED; PG8_LDA(At, 1, 0); PG8_STAGE(PG8_SA(0, 1), a2 + hstep, voffA);
;             PG8_WAIT_V(8); PG8_WAIT_L(0); PG8_BAR; PG8_MMA(0, 0, At, B0); PG8_MMA(0, 1, At, B1); PG8_BAR; PG8_SCHED;
	v_mfma_f32_16x16x32_bf16 v[60:63], v[128:131], v[172:175], v[60:63]
	v_mfma_f32_16x16x32_bf16 v[56:59], v[136:139], v[172:175], v[56:59]
	v_mfma_f32_16x16x32_bf16 v[52:55], v[128:131], v[186:189], v[52:55]
	v_mfma_f32_16x16x32_bf16 v[48:51], v[136:139], v[186:189], v[48:51]
	v_mfma_f32_16x16x32_bf16 v[36:39], v[128:131], v[194:197], v[36:39]
	v_mfma_f32_16x16x32_bf16 v[32:35], v[136:139], v[194:197], v[32:35]
	v_mfma_f32_16x16x32_bf16 v[20:23], v[128:131], v[202:205], v[20:23]
	v_mfma_f32_16x16x32_bf16 v[16:19], v[136:139], v[202:205], v[16:19]
	v_mfma_f32_16x16x32_bf16 v[60:63], v[132:135], v[182:185], v[60:63]
	v_mfma_f32_16x16x32_bf16 v[56:59], v[140:143], v[182:185], v[56:59]
	v_mfma_f32_16x16x32_bf16 v[52:55], v[132:135], v[190:193], v[52:55]
	v_mfma_f32_16x16x32_bf16 v[48:51], v[140:143], v[190:193], v[48:51]
	v_mfma_f32_16x16x32_bf16 v[36:39], v[132:135], v[198:201], v[36:39]
	v_mfma_f32_16x16x32_bf16 v[32:35], v[140:143], v[198:201], v[32:35]
	v_mfma_f32_16x16x32_bf16 v[20:23], v[132:135], v[208:211], v[20:23]
	v_mfma_f32_16x16x32_bf16 v[16:19], v[140:143], v[208:211], v[16:19]
	v_mfma_f32_16x16x32_bf16 v[44:47], v[144:147], v[172:175], v[44:47]
	v_mfma_f32_16x16x32_bf16 v[40:43], v[164:167], v[172:175], v[40:43]
	v_mfma_f32_16x16x32_bf16 v[28:31], v[144:147], v[186:189], v[28:31]
	v_mfma_f32_16x16x32_bf16 v[24:27], v[164:167], v[186:189], v[24:27]
	v_mfma_f32_16x16x32_bf16 v[12:15], v[144:147], v[194:197], v[12:15]
	v_mfma_f32_16x16x32_bf16 v[8:11], v[164:167], v[194:197], v[8:11]
	v_mfma_f32_16x16x32_bf16 v[4:7], v[144:147], v[202:205], v[4:7]
	v_mfma_f32_16x16x32_bf16 v[0:3], v[164:167], v[202:205], v[0:3]
	v_mfma_f32_16x16x32_bf16 v[44:47], v[160:163], v[182:185], v[44:47]
	v_mfma_f32_16x16x32_bf16 v[40:43], v[168:171], v[182:185], v[40:43]
	v_mfma_f32_16x16x32_bf16 v[28:31], v[160:163], v[190:193], v[28:31]
	v_mfma_f32_16x16x32_bf16 v[24:27], v[168:171], v[190:193], v[24:27]
	v_mfma_f32_16x16x32_bf16 v[12:15], v[160:163], v[198:201], v[12:15]
	v_mfma_f32_16x16x32_bf16 v[8:11], v[168:171], v[198:201], v[8:11]
	v_mfma_f32_16x16x32_bf16 v[4:7], v[160:163], v[208:211], v[4:7]
	v_mfma_f32_16x16x32_bf16 v[0:3], v[168:171], v[208:211], v[0:3]
	s_barrier
	v_add_u32_e32 v140, s96, v177
	v_add_u32_e32 v168, s90, v177
	ds_read_b128 v[128:131], v140
	ds_read_b128 v[132:135], v140 offset:1024
	ds_read_b128 v[136:139], v140 offset:2048
	ds_read_b128 v[140:143], v140 offset:3072
	ds_read_b128 v[144:147], v168
	ds_read_b128 v[160:163], v168 offset:1024
	ds_read_b128 v[164:167], v168 offset:2048
	ds_read_b128 v[168:171], v168 offset:3072
	s_add_u32 s18, s20, 0x164000
	s_addc_u32 s19, s21, 0
	s_mov_b32 m0, s29
	v_lshl_add_u64 v[220:221], s[18:19], 0, v[148:149]
	ds_read_b128 v[172:175], v181 offset:32768
	ds_read_b128 v[182:185], v181 offset:33792
	ds_read_b128 v[186:189], v181 offset:34816
	ds_read_b128 v[190:193], v181 offset:35840
	ds_read_b128 v[194:197], v181 offset:36864
	ds_read_b128 v[198:201], v181 offset:37888
	ds_read_b128 v[202:205], v181 offset:38912
	ds_read_b128 v[208:211], v181 offset:39936
	global_load_lds_dwordx4 v[220:221], off
	v_lshl_add_u64 v[220:221], s[18:19], 0, v[152:153]
	s_mov_b32 m0, s97
	s_nop 0
	global_load_lds_dwordx4 v[220:221], off
	s_waitcnt vmcnt(8)
	s_waitcnt lgkmcnt(0)
	s_barrier
	v_mfma_f32_16x16x32_bf16 v[124:127], v[128:131], v[172:175], v[124:127]
	v_mfma_f32_16x16x32_bf16 v[120:123], v[136:139], v[172:175], v[120:123]
	v_mfma_f32_16x16x32_bf16 v[116:119], v[128:131], v[186:189], v[116:119]
	v_mfma_f32_16x16x32_bf16 v[112:115], v[136:139], v[186:189], v[112:115]
	v_mfma_f32_16x16x32_bf16 v[100:103], v[128:131], v[194:197], v[100:103]
	v_mfma_f32_16x16x32_bf16 v[96:99], v[136:139], v[194:197], v[96:99]
	v_mfma_f32_16x16x32_bf16 v[84:87], v[128:131], v[202:205], v[84:87]
	v_mfma_f32_16x16x32_bf16 v[80:83], v[136:139], v[202:205], v[80:83]
	v_mfma_f32_16x16x32_bf16 v[124:127], v[132:135], v[182:185], v[124:127]
	v_mfma_f32_16x16x32_bf16 v[120:123], v[140:143], v[182:185], v[120:123]
	v_mfma_f32_16x16x32_bf16 v[116:119], v[132:135], v[190:193], v[116:119]
	v_mfma_f32_16x16x32_bf16 v[112:115], v[140:143], v[190:193], v[112:115]
	v_mfma_f32_16x16x32_bf16 v[100:103], v[132:135], v[198:201], v[100:103]
	v_mfma_f32_16x16x32_bf16 v[96:99], v[140:143], v[198:201], v[96:99]
	v_mfma_f32_16x16x32_bf16 v[84:87], v[132:135], v[208:211], v[84:87]
	v_mfma_f32_16x16x32_bf16 v[80:83], v[140:143], v[208:211], v[80:83]
	v_mfma_f32_16x16x32_bf16 v[108:111], v[144:147], v[172:175], v[108:111]
	v_mfma_f32_16x16x32_bf16 v[104:107], v[164:167], v[172:175], v[104:107]
	v_mfma_f32_16x16x32_bf16 v[92:95], v[144:147], v[186:189], v[92:95]
	v_mfma_f32_16x16x32_bf16 v[88:91], v[164:167], v[186:189], v[88:91]
	v_mfma_f32_16x16x32_bf16 v[76:79], v[144:147], v[194:197], v[76:79]
	v_mfma_f32_16x16x32_bf16 v[72:75], v[164:167], v[194:197], v[72:75]
	v_mfma_f32_16x16x32_bf16 v[68:71], v[144:147], v[202:205], v[68:71]
	v_mfma_f32_16x16x32_bf16 v[64:67], v[164:167], v[202:205], v[64:67]
	v_mfma_f32_16x16x32_bf16 v[108:111], v[160:163], v[182:185], v[108:111]
	v_mfma_f32_16x16x32_bf16 v[104:107], v[168:171], v[182:185], v[104:107]
	v_mfma_f32_16x16x32_bf16 v[92:95], v[160:163], v[190:193], v[92:95]
	v_mfma_f32_16x16x32_bf16 v[88:91], v[168:171], v[190:193], v[88:91]
	v_mfma_f32_16x16x32_bf16 v[76:79], v[160:163], v[198:201], v[76:79]
	v_mfma_f32_16x16x32_bf16 v[72:75], v[168:171], v[198:201], v[72:75]
	v_mfma_f32_16x16x32_bf16 v[68:71], v[160:163], v[208:211], v[68:71]
	v_mfma_f32_16x16x32_bf16 v[64:67], v[168:171], v[208:211], v[64:67]
	s_barrier
; #define PG8_STAGE(bufoff, gbase, voff) do { _Pragma("unroll") for (int _i = 0; _i < 2; ++_i) \
;         __builtin_amdgcn_global_load_lds((const unsigned*)((const char*)(gbase) + (voff)[_i]), (LAS unsigned*)(lds + (bufoff) + ldsw + _i * 8192), 16, 0, 0); } while (0)
; #define PG8_LDA(dst, b, h) do { _Pragma("unroll") for (int m = 0; m < 4; ++m) _Pragma("unroll") for (int k = 0; k < 2; ++k) dst[m][k] = *(const LAS bf16x8*)(lds + PG8_SA(b, h) + aoff + m * 2048 + k * 1024); } while (0)
; #define PG8_MMA(ai, bj, At, Bt) do { __builtin_amdgcn_s_setprio(1); _Pragma("unroll") for (int m = 0; m < 4; ++m) _Pragma("unroll") for (int n = 0; n < 2; ++n) _Pragma("unroll") for (int k = 0; k < 2; ++k) \
;         acc[ai][bj][m][n] = __builtin_amdgcn_mfma_f32_16x16x32_bf16(Bt[n][k], At[m][k], acc[ai][bj][m][n], 0, 0, 0); __builtin_amdgcn_s_setprio(0); } while (0)
; #define PG8_WAIT_V(n) asm volatile("s_waitcnt vmcnt(" #n ")" ::: "memory")
; #define PG8_WAIT_L(n) asm volatile("s_waitcnt lgkmcnt(" #n ")" ::: "memory")
; #define PG8_BAR __builtin_amdgcn_s_barrier()
; #define PG8_SCHED __builtin_amdgcn_sched_barrier(0)
; template <class Epi, class Sched>
; DI void gemm_phase(LAS unsigned char* lds, const int K, const Sched& S, const Epi& E, const int wid) {
;     ...
;             PG8_LDA(At, 1, 1); PG8_STAGE(PG8_SB(1, 0), b3, voffB); PG8_STAGE(PG8_SB(1, 1), b3 + hstep, voffB); PG8_STAGE(PG8_SA(1, 0), a3, voffA);
;             PG8_WAIT_V(8); PG8_WAIT_L(0); PG8_BAR; PG8_MMA(1, 0, At, B0); PG8_MMA(1, 1, At, B1); PG8_BAR; PG8_SCHED;
;         }
;         if (wr == 0) PG8_BAR;
;         E(acc, cur, wr, wc, fr, fq);
	s_mov_b32 m0, s94
	v_lshl_add_u64 v[212:213], v[212:213], 0, s[10:11]
	s_add_u32 s6, s6, 0x164080
	ds_read_b128 v[172:175], v181 offset:49152
	ds_read_b128 v[182:185], v181 offset:50176
	ds_read_b128 v[186:189], v181 offset:51200
	ds_read_b128 v[190:193], v181 offset:52224
	ds_read_b128 v[194:197], v181 offset:53248
	ds_read_b128 v[198:201], v181 offset:54272
	ds_read_b128 v[202:205], v181 offset:55296
	ds_read_b128 v[208:211], v181 offset:56320
	global_load_lds_dwordx4 v[212:213], off
	v_lshl_add_u64 v[212:213], v[214:215], 0, s[10:11]
	s_mov_b32 m0, s84
	s_addc_u32 s7, s7, 0
	global_load_lds_dwordx4 v[212:213], off
	v_lshl_add_u64 v[212:213], s[6:7], 0, v[150:151]
	s_mov_b32 m0, s86
	s_nop 0
	global_load_lds_dwordx4 v[212:213], off
	v_lshl_add_u64 v[212:213], s[6:7], 0, v[154:155]
	s_mov_b32 m0, s28
	s_nop 0
	global_load_lds_dwordx4 v[212:213], off
	v_lshl_add_u64 v[212:213], v[216:217], 0, s[10:11]
	s_mov_b32 m0, s91
	s_nop 0
	global_load_lds_dwordx4 v[212:213], off
	v_lshl_add_u64 v[212:213], v[218:219], 0, s[10:11]
	s_mov_b32 m0, s88
	s_nop 0
	global_load_lds_dwordx4 v[212:213], off
	s_waitcnt vmcnt(8)
	s_waitcnt lgkmcnt(0)
	s_barrier
	v_mfma_f32_16x16x32_bf16 v[60:63], v[128:131], v[172:175], v[60:63]
	v_mfma_f32_16x16x32_bf16 v[56:59], v[136:139], v[172:175], v[56:59]
	v_mfma_f32_16x16x32_bf16 v[52:55], v[128:131], v[186:189], v[52:55]
	v_mfma_f32_16x16x32_bf16 v[48:51], v[136:139], v[186:189], v[48:51]
	v_mfma_f32_16x16x32_bf16 v[36:39], v[128:131], v[194:197], v[36:39]
	v_mfma_f32_16x16x32_bf16 v[32:35], v[136:139], v[194:197], v[32:35]
	v_mfma_f32_16x16x32_bf16 v[20:23], v[128:131], v[202:205], v[20:23]
	v_mfma_f32_16x16x32_bf16 v[16:19], v[136:139], v[202:205], v[16:19]
	v_mfma_f32_16x16x32_bf16 v[60:63], v[132:135], v[182:185], v[60:63]
	v_mfma_f32_16x16x32_bf16 v[56:59], v[140:143], v[182:185], v[56:59]
	v_mfma_f32_16x16x32_bf16 v[52:55], v[132:135], v[190:193], v[52:55]
	v_mfma_f32_16x16x32_bf16 v[48:51], v[140:143], v[190:193], v[48:51]
	v_mfma_f32_16x16x32_bf16 v[36:39], v[132:135], v[198:201], v[36:39]
	v_mfma_f32_16x16x32_bf16 v[32:35], v[140:143], v[198:201], v[32:35]
	v_mfma_f32_16x16x32_bf16 v[20:23], v[132:135], v[208:211], v[20:23]
	v_mfma_f32_16x16x32_bf16 v[16:19], v[140:143], v[208:211], v[16:19]
	v_mfma_f32_16x16x32_bf16 v[44:47], v[144:147], v[172:175], v[44:47]
	v_mfma_f32_16x16x32_bf16 v[40:43], v[164:167], v[172:175], v[40:43]
	v_mfma_f32_16x16x32_bf16 v[28:31], v[144:147], v[186:189], v[28:31]
	v_mfma_f32_16x16x32_bf16 v[24:27], v[164:167], v[186:189], v[24:27]
	v_mfma_f32_16x16x32_bf16 v[12:15], v[144:147], v[194:197], v[12:15]
	v_mfma_f32_16x16x32_bf16 v[8:11], v[164:167], v[194:197], v[8:11]
	v_mfma_f32_16x16x32_bf16 v[4:7], v[144:147], v[202:205], v[4:7]
	v_mfma_f32_16x16x32_bf16 v[0:3], v[164:167], v[202:205], v[0:3]
	v_mfma_f32_16x16x32_bf16 v[44:47], v[160:163], v[182:185], v[44:47]
	v_mfma_f32_16x16x32_bf16 v[40:43], v[168:171], v[182:185], v[40:43]
	v_mfma_f32_16x16x32_bf16 v[28:31], v[160:163], v[190:193], v[28:31]
	v_mfma_f32_16x16x32_bf16 v[24:27], v[168:171], v[190:193], v[24:27]
	v_mfma_f32_16x16x32_bf16 v[12:15], v[160:163], v[198:201], v[12:15]
	v_mfma_f32_16x16x32_bf16 v[8:11], v[168:171], v[198:201], v[8:11]
	v_mfma_f32_16x16x32_bf16 v[4:7], v[160:163], v[208:211], v[4:7]
	v_mfma_f32_16x16x32_bf16 v[0:3], v[168:171], v[208:211], v[0:3]
	s_barrier
	s_add_u32 s36, s36, 0x100
	s_addc_u32 s37, s37, 0
	s_cmp_ge_u32 s38, s34
	s_mov_b64 s[18:19], s[4:5]
	s_mov_b32 s6, s38
	s_cbranch_scc0 .LBB0_1068
	v_readlane_b32 s4, v249, 25
	v_readlane_b32 s5, v249, 26
	s_and_b64 vcc, exec, s[4:5]
	s_cbranch_vccz .LBB0_1071
	s_barrier
